# combo14 = combo12 with every s_setprio removed from the GEMM K-loops
# speedup vs baseline: 1.0092x; 1.0092x over previous
; #define PG8_STAGE(bufoff, gbase, voff) do { _Pragma("unroll") for (int _i = 0; _i < 2; ++_i) \
;         __builtin_amdgcn_global_load_lds((const unsigned*)((const char*)(gbase) + (voff)[_i]), (PG8_LAS unsigned*)(lds + (bufoff) + ldsw + _i * 8192), 16, 0, 0); } while (0)
; #define PG8_LDA(dst, b, h) do { _Pragma("unroll") for (int m = 0; m < 4; ++m) _Pragma("unroll") for (int k = 0; k < 2; ++k) dst[m][k] = *(const PG8_LAS bf16x8*)(lds + PG8_SA(b, h) + aoff + m * 2048 + k * 1024); } while (0)
; #define PG8_LDB(dst, b, h) do { _Pragma("unroll") for (int n = 0; n < 2; ++n) _Pragma("unroll") for (int k = 0; k < 2; ++k) dst[n][k] = *(const PG8_LAS bf16x8*)(lds + PG8_SB(b, h) + boff + n * 2048 + k * 1024); } while (0)
; #define PG8_MMA(ai, bj, At, Bt) do { __builtin_amdgcn_s_setprio(1); _Pragma("unroll") for (int m = 0; m < 4; ++m) _Pragma("unroll") for (int n = 0; n < 2; ++n) _Pragma("unroll") for (int k = 0; k < 2; ++k) \
;         acc[ai][bj][m][n] = __builtin_amdgcn_mfma_f32_16x16x32_bf16(Bt[n][k], At[m][k], acc[ai][bj][m][n], 0, 0, 0); __builtin_amdgcn_s_setprio(0); } while (0)
; #define PG8_WAIT_V(n) asm volatile("s_waitcnt vmcnt(" #n ")" ::: "memory")
; #define PG8_WAIT_L(n) asm volatile("s_waitcnt lgkmcnt(" #n ")" ::: "memory")
; #define PG8_BAR __builtin_amdgcn_s_barrier()
; #define PG8_SCHED __builtin_amdgcn_sched_barrier(0)
; template <class Epi, class Sched, bool ALIGN_EPI = false, bool SP2 = false>
; __device__ __forceinline__ void gemm_phase(PG8_LAS unsigned char* lds, const Gemm g, const Sched& S, const Epi& E) {
;     ...
;             PG8_LDB(B0, 0, 0); PG8_LDB(B1, 0, 1); PG8_SCHED; PG8_LDA(At, 0, 0); PG8_STAGE(PG8_SA(1, 1), a1 + hstep, voffA);
;             PG8_WAIT_V(8); PG8_WAIT_L(0); PG8_BAR; PG8_MMA(0, 0, At, B0); PG8_MMA(0, 1, At, B1); PG8_BAR; PG8_SCHED;
;             PG8_LDA(At, 0, 1); PG8_STAGE(PG8_SB(0, 0), b2, voffB); PG8_STAGE(PG8_SB(0, 1), b2 + hstep, voffB); PG8_STAGE(PG8_SA(0, 0), a2, voffA);
;             PG8_WAIT_V(8); PG8_WAIT_L(0); PG8_BAR; PG8_MMA(1, 0, At, B0); PG8_MMA(1, 1, At, B1); PG8_BAR; PG8_SCHED;
.LBB0_424:
	s_add_u32 s66, s8, 0xfff80080
	s_addc_u32 s67, s9, -1
	s_add_i32 s72, 0, 0x10000
	s_cmp_eq_u32 s29, 28
	s_cselect_b32 s97, s14, s67
	s_cselect_b32 s96, s15, s66
	v_add_u32_e32 v128, s72, v187
	s_cselect_b32 s67, s16, s19
	s_cselect_b32 s66, s17, s18
	s_add_i32 s90, 0, 0x14000
	ds_read_b128 v[134:137], v128
	ds_read_b128 v[138:141], v128 offset:1024
	ds_read_b128 v[142:145], v128 offset:2048
	ds_read_b128 v[166:169], v128 offset:3072
	v_add_u32_e32 v128, s90, v187
	ds_read_b128 v[170:173], v128
	ds_read_b128 v[174:177], v128 offset:1024
	ds_read_b128 v[178:181], v128 offset:2048
	ds_read_b128 v[182:185], v128 offset:3072
	v_lshl_add_u64 v[222:223], s[8:9], 0, v[158:159]
	s_add_i32 m0, s13, 0xc000
	ds_read_b128 v[190:193], v189
	ds_read_b128 v[194:197], v189 offset:1024
	ds_read_b128 v[198:201], v189 offset:2048
	ds_read_b128 v[202:205], v189 offset:3072
	ds_read_b128 v[206:209], v189 offset:4096
	ds_read_b128 v[210:213], v189 offset:5120
	ds_read_b128 v[214:217], v189 offset:6144
	ds_read_b128 v[218:221], v189 offset:7168
	global_load_lds_dwordx4 v[222:223], off
	v_lshl_add_u64 v[222:223], s[8:9], 0, v[156:157]
	s_add_i32 m0, s13, 0xe000
	s_nop 0
	global_load_lds_dwordx4 v[222:223], off
	s_waitcnt vmcnt(8)
	s_waitcnt lgkmcnt(0)
	s_barrier
	v_mfma_f32_16x16x32_bf16 v[130:133], v[134:137], v[190:193], v[130:133]
	v_mfma_f32_16x16x32_bf16 v[124:127], v[142:145], v[190:193], v[124:127]
	v_mfma_f32_16x16x32_bf16 v[116:119], v[134:137], v[198:201], v[116:119]
	v_mfma_f32_16x16x32_bf16 v[108:111], v[142:145], v[198:201], v[108:111]
	v_mfma_f32_16x16x32_bf16 v[100:103], v[134:137], v[206:209], v[100:103]
	v_mfma_f32_16x16x32_bf16 v[92:95], v[142:145], v[206:209], v[92:95]
	v_mfma_f32_16x16x32_bf16 v[84:87], v[134:137], v[214:217], v[84:87]
	v_mfma_f32_16x16x32_bf16 v[76:79], v[142:145], v[214:217], v[76:79]
	v_mfma_f32_16x16x32_bf16 v[130:133], v[138:141], v[194:197], v[130:133]
	v_mfma_f32_16x16x32_bf16 v[124:127], v[166:169], v[194:197], v[124:127]
	v_mfma_f32_16x16x32_bf16 v[116:119], v[138:141], v[202:205], v[116:119]
	v_mfma_f32_16x16x32_bf16 v[108:111], v[166:169], v[202:205], v[108:111]
	v_mfma_f32_16x16x32_bf16 v[100:103], v[138:141], v[210:213], v[100:103]
	v_mfma_f32_16x16x32_bf16 v[92:95], v[166:169], v[210:213], v[92:95]
	v_mfma_f32_16x16x32_bf16 v[84:87], v[138:141], v[218:221], v[84:87]
	v_mfma_f32_16x16x32_bf16 v[76:79], v[166:169], v[218:221], v[76:79]
	v_mfma_f32_16x16x32_bf16 v[120:123], v[170:173], v[190:193], v[120:123]
	v_mfma_f32_16x16x32_bf16 v[112:115], v[178:181], v[190:193], v[112:115]
	v_mfma_f32_16x16x32_bf16 v[104:107], v[170:173], v[198:201], v[104:107]
	v_mfma_f32_16x16x32_bf16 v[96:99], v[178:181], v[198:201], v[96:99]
	v_mfma_f32_16x16x32_bf16 v[88:91], v[170:173], v[206:209], v[88:91]
	v_mfma_f32_16x16x32_bf16 v[80:83], v[178:181], v[206:209], v[80:83]
	v_mfma_f32_16x16x32_bf16 v[72:75], v[170:173], v[214:217], v[72:75]
	v_mfma_f32_16x16x32_bf16 v[68:71], v[178:181], v[214:217], v[68:71]
	v_mfma_f32_16x16x32_bf16 v[120:123], v[174:177], v[194:197], v[120:123]
	v_mfma_f32_16x16x32_bf16 v[112:115], v[182:185], v[194:197], v[112:115]
	v_mfma_f32_16x16x32_bf16 v[104:107], v[174:177], v[202:205], v[104:107]
	v_mfma_f32_16x16x32_bf16 v[96:99], v[182:185], v[202:205], v[96:99]
	v_mfma_f32_16x16x32_bf16 v[88:91], v[174:177], v[210:213], v[88:91]
	v_mfma_f32_16x16x32_bf16 v[80:83], v[182:185], v[210:213], v[80:83]
	v_mfma_f32_16x16x32_bf16 v[72:75], v[174:177], v[218:221], v[72:75]
	v_mfma_f32_16x16x32_bf16 v[68:71], v[182:185], v[218:221], v[68:71]
	s_barrier
	s_add_i32 s72, s72, s20
	v_lshl_add_u64 v[222:223], s[66:67], 0, v[150:151]
	s_mov_b32 m0, s72
	ds_read_b128 v[190:193], v189 offset:16384
	ds_read_b128 v[194:197], v189 offset:17408
	ds_read_b128 v[198:201], v189 offset:18432
	ds_read_b128 v[202:205], v189 offset:19456
	ds_read_b128 v[206:209], v189 offset:20480
	ds_read_b128 v[210:213], v189 offset:21504
	ds_read_b128 v[214:217], v189 offset:22528
	ds_read_b128 v[218:221], v189 offset:23552
	global_load_lds_dwordx4 v[222:223], off
	s_add_i32 m0, s72, 0x2000
	s_add_u32 s72, s66, 0x80000
	v_lshl_add_u64 v[224:225], s[66:67], 0, v[146:147]
	s_addc_u32 s73, s67, 0
	s_add_i32 s90, s90, s20
	global_load_lds_dwordx4 v[224:225], off
	v_lshl_add_u64 v[226:227], s[72:73], 0, v[150:151]
	s_mov_b32 m0, s90
	v_lshl_add_u64 v[228:229], s[96:97], 0, v[148:149]
	global_load_lds_dwordx4 v[226:227], off
	v_lshl_add_u64 v[226:227], s[72:73], 0, v[146:147]
	s_add_i32 m0, s90, 0x2000
	s_nop 0
	global_load_lds_dwordx4 v[226:227], off
	v_lshl_add_u64 v[226:227], s[96:97], 0, v[152:153]
	s_mov_b32 m0, s13
	s_nop 0
	global_load_lds_dwordx4 v[226:227], off
	s_mov_b32 m0, s23
	s_nop 0
	global_load_lds_dwordx4 v[228:229], off
	s_waitcnt vmcnt(8)
	s_waitcnt lgkmcnt(0)
	s_barrier
; #define PG8_STAGE(bufoff, gbase, voff) do { _Pragma("unroll") for (int _i = 0; _i < 2; ++_i) \
;         __builtin_amdgcn_global_load_lds((const unsigned*)((const char*)(gbase) + (voff)[_i]), (PG8_LAS unsigned*)(lds + (bufoff) + ldsw + _i * 8192), 16, 0, 0); } while (0)
; #define PG8_LDA(dst, b, h) do { _Pragma("unroll") for (int m = 0; m < 4; ++m) _Pragma("unroll") for (int k = 0; k < 2; ++k) dst[m][k] = *(const PG8_LAS bf16x8*)(lds + PG8_SA(b, h) + aoff + m * 2048 + k * 1024); } while (0)
; #define PG8_LDB(dst, b, h) do { _Pragma("unroll") for (int n = 0; n < 2; ++n) _Pragma("unroll") for (int k = 0; k < 2; ++k) dst[n][k] = *(const PG8_LAS bf16x8*)(lds + PG8_SB(b, h) + boff + n * 2048 + k * 1024); } while (0)
; #define PG8_MMA(ai, bj, At, Bt) do { __builtin_amdgcn_s_setprio(1); _Pragma("unroll") for (int m = 0; m < 4; ++m) _Pragma("unroll") for (int n = 0; n < 2; ++n) _Pragma("unroll") for (int k = 0; k < 2; ++k) \
;         acc[ai][bj][m][n] = __builtin_amdgcn_mfma_f32_16x16x32_bf16(Bt[n][k], At[m][k], acc[ai][bj][m][n], 0, 0, 0); __builtin_amdgcn_s_setprio(0); } while (0)
; #define PG8_WAIT_V(n) asm volatile("s_waitcnt vmcnt(" #n ")" ::: "memory")
; #define PG8_WAIT_L(n) asm volatile("s_waitcnt lgkmcnt(" #n ")" ::: "memory")
; #define PG8_BAR __builtin_amdgcn_s_barrier()
; #define PG8_SCHED __builtin_amdgcn_sched_barrier(0)
; template <class Epi, class Sched, bool ALIGN_EPI = false, bool SP2 = false>
; __device__ __forceinline__ void gemm_phase(PG8_LAS unsigned char* lds, const Gemm g, const Sched& S, const Epi& E) {
;     ...
;             PG8_WAIT_V(8); PG8_WAIT_L(0); PG8_BAR; PG8_MMA(1, 0, At, B0); PG8_MMA(1, 1, At, B1); PG8_BAR; PG8_SCHED;
;             PG8_LDB(B0, 1, 0); PG8_LDB(B1, 1, 1); PG8_SCHED; PG8_LDA(At, 1, 0); PG8_STAGE(PG8_SA(0, 1), a2 + hstep, voffA);
;             PG8_WAIT_V(8); PG8_WAIT_L(0); PG8_BAR; PG8_MMA(0, 0, At, B0); PG8_MMA(0, 1, At, B1); PG8_BAR; PG8_SCHED;
	v_mfma_f32_16x16x32_bf16 v[64:67], v[134:137], v[190:193], v[64:67]
	v_mfma_f32_16x16x32_bf16 v[60:63], v[142:145], v[190:193], v[60:63]
	v_mfma_f32_16x16x32_bf16 v[52:55], v[134:137], v[198:201], v[52:55]
	v_mfma_f32_16x16x32_bf16 v[44:47], v[142:145], v[198:201], v[44:47]
	v_mfma_f32_16x16x32_bf16 v[32:35], v[134:137], v[206:209], v[32:35]
	v_mfma_f32_16x16x32_bf16 v[24:27], v[142:145], v[206:209], v[24:27]
	v_mfma_f32_16x16x32_bf16 v[16:19], v[134:137], v[214:217], v[16:19]
	v_mfma_f32_16x16x32_bf16 v[8:11], v[142:145], v[214:217], v[8:11]
	v_mfma_f32_16x16x32_bf16 v[64:67], v[138:141], v[194:197], v[64:67]
	v_mfma_f32_16x16x32_bf16 v[60:63], v[166:169], v[194:197], v[60:63]
	v_mfma_f32_16x16x32_bf16 v[52:55], v[138:141], v[202:205], v[52:55]
	v_mfma_f32_16x16x32_bf16 v[44:47], v[166:169], v[202:205], v[44:47]
	v_mfma_f32_16x16x32_bf16 v[32:35], v[138:141], v[210:213], v[32:35]
	v_mfma_f32_16x16x32_bf16 v[24:27], v[166:169], v[210:213], v[24:27]
	v_mfma_f32_16x16x32_bf16 v[16:19], v[138:141], v[218:221], v[16:19]
	v_mfma_f32_16x16x32_bf16 v[8:11], v[166:169], v[218:221], v[8:11]
	v_mfma_f32_16x16x32_bf16 v[56:59], v[170:173], v[190:193], v[56:59]
	v_mfma_f32_16x16x32_bf16 v[48:51], v[178:181], v[190:193], v[48:51]
	v_mfma_f32_16x16x32_bf16 v[36:39], v[170:173], v[198:201], v[36:39]
	v_mfma_f32_16x16x32_bf16 v[28:31], v[178:181], v[198:201], v[28:31]
	v_mfma_f32_16x16x32_bf16 v[20:23], v[170:173], v[206:209], v[20:23]
	v_mfma_f32_16x16x32_bf16 v[12:15], v[178:181], v[206:209], v[12:15]
	v_mfma_f32_16x16x32_bf16 v[4:7], v[170:173], v[214:217], v[4:7]
	v_mfma_f32_16x16x32_bf16 v[0:3], v[178:181], v[214:217], v[0:3]
	v_mfma_f32_16x16x32_bf16 v[56:59], v[174:177], v[194:197], v[56:59]
	v_mfma_f32_16x16x32_bf16 v[48:51], v[182:185], v[194:197], v[48:51]
	v_mfma_f32_16x16x32_bf16 v[36:39], v[174:177], v[202:205], v[36:39]
	v_mfma_f32_16x16x32_bf16 v[28:31], v[182:185], v[202:205], v[28:31]
	v_mfma_f32_16x16x32_bf16 v[20:23], v[174:177], v[210:213], v[20:23]
	v_mfma_f32_16x16x32_bf16 v[12:15], v[182:185], v[210:213], v[12:15]
	v_mfma_f32_16x16x32_bf16 v[4:7], v[174:177], v[218:221], v[4:7]
	v_mfma_f32_16x16x32_bf16 v[0:3], v[182:185], v[218:221], v[0:3]
	s_barrier
	s_add_i32 s90, 0, 0x18000
	v_add_u32_e32 v128, s90, v187
	s_add_i32 s91, 0, 0x1c000
	ds_read_b128 v[134:137], v128
	ds_read_b128 v[138:141], v128 offset:1024
	ds_read_b128 v[142:145], v128 offset:2048
	ds_read_b128 v[166:169], v128 offset:3072
	v_add_u32_e32 v128, s91, v187
	ds_read_b128 v[170:173], v128
	ds_read_b128 v[174:177], v128 offset:1024
	ds_read_b128 v[178:181], v128 offset:2048
	ds_read_b128 v[182:185], v128 offset:3072
	s_add_u32 s72, s96, 0x80000
	s_addc_u32 s73, s97, 0
	s_mov_b32 m0, s24
	v_lshl_add_u64 v[230:231], s[72:73], 0, v[152:153]
	ds_read_b128 v[190:193], v189 offset:32768
	ds_read_b128 v[194:197], v189 offset:33792
	ds_read_b128 v[198:201], v189 offset:34816
	ds_read_b128 v[202:205], v189 offset:35840
	ds_read_b128 v[206:209], v189 offset:36864
	ds_read_b128 v[210:213], v189 offset:37888
	ds_read_b128 v[214:217], v189 offset:38912
	ds_read_b128 v[218:221], v189 offset:39936
	global_load_lds_dwordx4 v[230:231], off
	v_lshl_add_u64 v[230:231], s[72:73], 0, v[148:149]
	s_mov_b32 m0, s25
	s_nop 0
	global_load_lds_dwordx4 v[230:231], off
	s_waitcnt vmcnt(8)
	s_waitcnt lgkmcnt(0)
	s_barrier
	v_mfma_f32_16x16x32_bf16 v[130:133], v[134:137], v[190:193], v[130:133]
	v_mfma_f32_16x16x32_bf16 v[124:127], v[142:145], v[190:193], v[124:127]
	v_mfma_f32_16x16x32_bf16 v[116:119], v[134:137], v[198:201], v[116:119]
	v_mfma_f32_16x16x32_bf16 v[108:111], v[142:145], v[198:201], v[108:111]
	v_mfma_f32_16x16x32_bf16 v[100:103], v[134:137], v[206:209], v[100:103]
	v_mfma_f32_16x16x32_bf16 v[92:95], v[142:145], v[206:209], v[92:95]
	v_mfma_f32_16x16x32_bf16 v[84:87], v[134:137], v[214:217], v[84:87]
	v_mfma_f32_16x16x32_bf16 v[76:79], v[142:145], v[214:217], v[76:79]
	v_mfma_f32_16x16x32_bf16 v[130:133], v[138:141], v[194:197], v[130:133]
	v_mfma_f32_16x16x32_bf16 v[124:127], v[166:169], v[194:197], v[124:127]
	v_mfma_f32_16x16x32_bf16 v[116:119], v[138:141], v[202:205], v[116:119]
	v_mfma_f32_16x16x32_bf16 v[108:111], v[166:169], v[202:205], v[108:111]
	v_mfma_f32_16x16x32_bf16 v[100:103], v[138:141], v[210:213], v[100:103]
	v_mfma_f32_16x16x32_bf16 v[92:95], v[166:169], v[210:213], v[92:95]
	v_mfma_f32_16x16x32_bf16 v[84:87], v[138:141], v[218:221], v[84:87]
	v_mfma_f32_16x16x32_bf16 v[76:79], v[166:169], v[218:221], v[76:79]
	v_mfma_f32_16x16x32_bf16 v[120:123], v[170:173], v[190:193], v[120:123]
	v_mfma_f32_16x16x32_bf16 v[112:115], v[178:181], v[190:193], v[112:115]
	v_mfma_f32_16x16x32_bf16 v[104:107], v[170:173], v[198:201], v[104:107]
	v_mfma_f32_16x16x32_bf16 v[96:99], v[178:181], v[198:201], v[96:99]
	v_mfma_f32_16x16x32_bf16 v[88:91], v[170:173], v[206:209], v[88:91]
	v_mfma_f32_16x16x32_bf16 v[80:83], v[178:181], v[206:209], v[80:83]
	v_mfma_f32_16x16x32_bf16 v[72:75], v[170:173], v[214:217], v[72:75]
	v_mfma_f32_16x16x32_bf16 v[68:71], v[178:181], v[214:217], v[68:71]
	v_mfma_f32_16x16x32_bf16 v[120:123], v[174:177], v[194:197], v[120:123]
	v_mfma_f32_16x16x32_bf16 v[112:115], v[182:185], v[194:197], v[112:115]
	v_mfma_f32_16x16x32_bf16 v[104:107], v[174:177], v[202:205], v[104:107]
	v_mfma_f32_16x16x32_bf16 v[96:99], v[182:185], v[202:205], v[96:99]
	v_mfma_f32_16x16x32_bf16 v[88:91], v[174:177], v[210:213], v[88:91]
	v_mfma_f32_16x16x32_bf16 v[80:83], v[182:185], v[210:213], v[80:83]
	v_mfma_f32_16x16x32_bf16 v[72:75], v[174:177], v[218:221], v[72:75]
	v_mfma_f32_16x16x32_bf16 v[68:71], v[182:185], v[218:221], v[68:71]
	s_barrier
; #define PG8_STAGE(bufoff, gbase, voff) do { _Pragma("unroll") for (int _i = 0; _i < 2; ++_i) \
;         __builtin_amdgcn_global_load_lds((const unsigned*)((const char*)(gbase) + (voff)[_i]), (PG8_LAS unsigned*)(lds + (bufoff) + ldsw + _i * 8192), 16, 0, 0); } while (0)
; #define PG8_LDA(dst, b, h) do { _Pragma("unroll") for (int m = 0; m < 4; ++m) _Pragma("unroll") for (int k = 0; k < 2; ++k) dst[m][k] = *(const PG8_LAS bf16x8*)(lds + PG8_SA(b, h) + aoff + m * 2048 + k * 1024); } while (0)
; #define PG8_MMA(ai, bj, At, Bt) do { __builtin_amdgcn_s_setprio(1); _Pragma("unroll") for (int m = 0; m < 4; ++m) _Pragma("unroll") for (int n = 0; n < 2; ++n) _Pragma("unroll") for (int k = 0; k < 2; ++k) \
;         acc[ai][bj][m][n] = __builtin_amdgcn_mfma_f32_16x16x32_bf16(Bt[n][k], At[m][k], acc[ai][bj][m][n], 0, 0, 0); __builtin_amdgcn_s_setprio(0); } while (0)
; #define PG8_WAIT_V(n) asm volatile("s_waitcnt vmcnt(" #n ")" ::: "memory")
; #define PG8_WAIT_L(n) asm volatile("s_waitcnt lgkmcnt(" #n ")" ::: "memory")
; #define PG8_BAR __builtin_amdgcn_s_barrier()
; #define PG8_SCHED __builtin_amdgcn_sched_barrier(0)
; template <class Epi, class Sched, bool ALIGN_EPI = false, bool SP2 = false>
; __device__ __forceinline__ void gemm_phase(PG8_LAS unsigned char* lds, const Gemm g, const Sched& S, const Epi& E) {
;     ...
;             PG8_LDA(At, 1, 1); PG8_STAGE(PG8_SB(1, 0), b3, voffB); PG8_STAGE(PG8_SB(1, 1), b3 + hstep, voffB); PG8_STAGE(PG8_SA(1, 0), a3, voffA);
;             PG8_WAIT_V(8); PG8_WAIT_L(0); PG8_BAR; PG8_MMA(1, 0, At, B0); PG8_MMA(1, 1, At, B1); PG8_BAR; PG8_SCHED;
;     ...
;         if constexpr (ALIGN_EPI) { if (wr == 0) PG8_BAR; }
	s_add_i32 s72, s90, s20
	v_lshl_add_u64 v[222:223], v[222:223], 0, s[76:77]
	s_mov_b32 m0, s72
	ds_read_b128 v[190:193], v189 offset:49152
	ds_read_b128 v[194:197], v189 offset:50176
	ds_read_b128 v[198:201], v189 offset:51200
	ds_read_b128 v[202:205], v189 offset:52224
	ds_read_b128 v[206:209], v189 offset:53248
	ds_read_b128 v[210:213], v189 offset:54272
	ds_read_b128 v[214:217], v189 offset:55296
	ds_read_b128 v[218:221], v189 offset:56320
	global_load_lds_dwordx4 v[222:223], off
	s_add_i32 m0, s72, 0x2000
	s_add_u32 s66, s66, 0x80080
	v_lshl_add_u64 v[222:223], v[224:225], 0, s[76:77]
	s_addc_u32 s67, s67, 0
	s_add_i32 s72, s91, s20
	global_load_lds_dwordx4 v[222:223], off
	v_lshl_add_u64 v[222:223], s[66:67], 0, v[150:151]
	s_mov_b32 m0, s72
	s_nop 0
	global_load_lds_dwordx4 v[222:223], off
	v_lshl_add_u64 v[222:223], s[66:67], 0, v[146:147]
	s_add_i32 m0, s72, 0x2000
	s_nop 0
	global_load_lds_dwordx4 v[222:223], off
	v_lshl_add_u64 v[222:223], v[226:227], 0, s[76:77]
	s_mov_b32 m0, s26
	s_nop 0
	global_load_lds_dwordx4 v[222:223], off
	v_lshl_add_u64 v[222:223], v[228:229], 0, s[76:77]
	s_mov_b32 m0, s27
	s_nop 0
	global_load_lds_dwordx4 v[222:223], off
	s_waitcnt vmcnt(8)
	s_waitcnt lgkmcnt(0)
	s_barrier
	v_mfma_f32_16x16x32_bf16 v[64:67], v[134:137], v[190:193], v[64:67]
	v_mfma_f32_16x16x32_bf16 v[60:63], v[142:145], v[190:193], v[60:63]
	v_mfma_f32_16x16x32_bf16 v[52:55], v[134:137], v[198:201], v[52:55]
	v_mfma_f32_16x16x32_bf16 v[44:47], v[142:145], v[198:201], v[44:47]
	v_mfma_f32_16x16x32_bf16 v[32:35], v[134:137], v[206:209], v[32:35]
	v_mfma_f32_16x16x32_bf16 v[24:27], v[142:145], v[206:209], v[24:27]
	v_mfma_f32_16x16x32_bf16 v[16:19], v[134:137], v[214:217], v[16:19]
	v_mfma_f32_16x16x32_bf16 v[8:11], v[142:145], v[214:217], v[8:11]
	v_mfma_f32_16x16x32_bf16 v[64:67], v[138:141], v[194:197], v[64:67]
	v_mfma_f32_16x16x32_bf16 v[60:63], v[166:169], v[194:197], v[60:63]
	v_mfma_f32_16x16x32_bf16 v[52:55], v[138:141], v[202:205], v[52:55]
	v_mfma_f32_16x16x32_bf16 v[44:47], v[166:169], v[202:205], v[44:47]
	v_mfma_f32_16x16x32_bf16 v[32:35], v[138:141], v[210:213], v[32:35]
	v_mfma_f32_16x16x32_bf16 v[24:27], v[166:169], v[210:213], v[24:27]
	v_mfma_f32_16x16x32_bf16 v[16:19], v[138:141], v[218:221], v[16:19]
	v_mfma_f32_16x16x32_bf16 v[8:11], v[166:169], v[218:221], v[8:11]
	v_mfma_f32_16x16x32_bf16 v[56:59], v[170:173], v[190:193], v[56:59]
	v_mfma_f32_16x16x32_bf16 v[48:51], v[178:181], v[190:193], v[48:51]
	v_mfma_f32_16x16x32_bf16 v[36:39], v[170:173], v[198:201], v[36:39]
	v_mfma_f32_16x16x32_bf16 v[28:31], v[178:181], v[198:201], v[28:31]
	v_mfma_f32_16x16x32_bf16 v[20:23], v[170:173], v[206:209], v[20:23]
	v_mfma_f32_16x16x32_bf16 v[12:15], v[178:181], v[206:209], v[12:15]
	v_mfma_f32_16x16x32_bf16 v[4:7], v[170:173], v[214:217], v[4:7]
	v_mfma_f32_16x16x32_bf16 v[0:3], v[178:181], v[214:217], v[0:3]
	v_mfma_f32_16x16x32_bf16 v[56:59], v[174:177], v[194:197], v[56:59]
	v_mfma_f32_16x16x32_bf16 v[48:51], v[182:185], v[194:197], v[48:51]
	v_mfma_f32_16x16x32_bf16 v[36:39], v[174:177], v[202:205], v[36:39]
	v_mfma_f32_16x16x32_bf16 v[28:31], v[182:185], v[202:205], v[28:31]
	v_mfma_f32_16x16x32_bf16 v[20:23], v[174:177], v[210:213], v[20:23]
	v_mfma_f32_16x16x32_bf16 v[12:15], v[182:185], v[210:213], v[12:15]
	v_mfma_f32_16x16x32_bf16 v[4:7], v[174:177], v[218:221], v[4:7]
	v_mfma_f32_16x16x32_bf16 v[0:3], v[182:185], v[218:221], v[0:3]
	s_barrier
	s_add_i32 s29, s29, 2
	s_add_u32 s18, s18, 0x100
	s_addc_u32 s19, s19, 0
	s_add_u32 s8, s8, 0x100
	s_addc_u32 s9, s9, 0
	s_cmp_gt_u32 s29, 29
	s_cbranch_scc0 .LBB0_424
	s_and_b64 vcc, exec, s[70:71]
	s_cbranch_vccz .LBB0_427
	s_barrier

; #define PG8_STAGE(bufoff, gbase, voff) do { _Pragma("unroll") for (int _i = 0; _i < 2; ++_i) \
;         __builtin_amdgcn_global_load_lds((const unsigned*)((const char*)(gbase) + (voff)[_i]), (PG8_LAS unsigned*)(lds + (bufoff) + ldsw + _i * 8192), 16, 0, 0); } while (0)
; #define PG8_LDA(dst, b, h) do { _Pragma("unroll") for (int m = 0; m < 4; ++m) _Pragma("unroll") for (int k = 0; k < 2; ++k) dst[m][k] = *(const PG8_LAS bf16x8*)(lds + PG8_SA(b, h) + aoff + m * 2048 + k * 1024); } while (0)
; #define PG8_LDB(dst, b, h) do { _Pragma("unroll") for (int n = 0; n < 2; ++n) _Pragma("unroll") for (int k = 0; k < 2; ++k) dst[n][k] = *(const PG8_LAS bf16x8*)(lds + PG8_SB(b, h) + boff + n * 2048 + k * 1024); } while (0)
; #define PG8_MMA(ai, bj, At, Bt) do { __builtin_amdgcn_s_setprio(1); _Pragma("unroll") for (int m = 0; m < 4; ++m) _Pragma("unroll") for (int n = 0; n < 2; ++n) _Pragma("unroll") for (int k = 0; k < 2; ++k) \
;         acc[ai][bj][m][n] = __builtin_amdgcn_mfma_f32_16x16x32_bf16(Bt[n][k], At[m][k], acc[ai][bj][m][n], 0, 0, 0); __builtin_amdgcn_s_setprio(0); } while (0)
; #define PG8_WAIT_V(n) asm volatile("s_waitcnt vmcnt(" #n ")" ::: "memory")
; #define PG8_WAIT_L(n) asm volatile("s_waitcnt lgkmcnt(" #n ")" ::: "memory")
; #define PG8_BAR __builtin_amdgcn_s_barrier()
; #define PG8_SCHED __builtin_amdgcn_sched_barrier(0)
; template <class Epi, class Sched, bool ALIGN_EPI = false, bool SP2 = false>
; __device__ __forceinline__ void gemm_phase(PG8_LAS unsigned char* lds, const Gemm g, const Sched& S, const Epi& E) {
;     ...
;             PG8_LDB(B0, 0, 0); PG8_LDB(B1, 0, 1); PG8_SCHED; PG8_LDA(At, 0, 0); PG8_STAGE(PG8_SA(1, 1), a1 + hstep, voffA);
;             PG8_WAIT_V(8); PG8_WAIT_L(0); PG8_BAR; PG8_MMA(0, 0, At, B0); PG8_MMA(0, 1, At, B1); PG8_BAR; PG8_SCHED;
;             PG8_LDA(At, 0, 1); PG8_STAGE(PG8_SB(0, 0), b2, voffB); PG8_STAGE(PG8_SB(0, 1), b2 + hstep, voffB); PG8_STAGE(PG8_SA(0, 0), a2, voffA);
;             PG8_WAIT_V(8); PG8_WAIT_L(0); PG8_BAR; PG8_MMA(1, 0, At, B0); PG8_MMA(1, 1, At, B1); PG8_BAR; PG8_SCHED;
.LBB0_458:
	s_add_i32 s96, s66, 2
	s_add_u32 s92, s10, 0x80
	s_addc_u32 s67, s11, 0
	s_add_i32 s93, 0, 0x10000
	s_cmp_eq_u32 s17, s66
	s_cselect_b32 s67, s71, s67
	s_cselect_b32 s66, s70, s92
	s_cselect_b32 vcc_hi, s95, s91
	s_cselect_b32 vcc_lo, s94, s13
	s_add_i32 s92, 0, 0x14000
	v_add_u32_e32 v84, s93, v229
	v_add_u32_e32 v134, s92, v229
	ds_read_b128 v[48:51], v84
	ds_read_b128 v[60:63], v84 offset:1024
	ds_read_b128 v[72:75], v84 offset:2048
	ds_read_b128 v[84:87], v84 offset:3072
	ds_read_b128 v[96:99], v134
	ds_read_b128 v[108:111], v134 offset:1024
	ds_read_b128 v[120:123], v134 offset:2048
	ds_read_b128 v[134:137], v134 offset:3072
	v_lshl_add_u64 v[208:209], s[10:11], 0, v[202:203]
	s_add_i32 m0, s26, 0xc000
	ds_read_b128 v[146:149], v231
	ds_read_b128 v[150:153], v231 offset:1024
	ds_read_b128 v[170:173], v231 offset:2048
	ds_read_b128 v[174:177], v231 offset:3072
	ds_read_b128 v[178:181], v231 offset:4096
	ds_read_b128 v[182:185], v231 offset:5120
	ds_read_b128 v[186:189], v231 offset:6144
	ds_read_b128 v[204:207], v231 offset:7168
	global_load_lds_dwordx4 v[208:209], off
	v_lshl_add_u64 v[208:209], s[10:11], 0, v[200:201]
	s_add_i32 m0, s26, 0xe000
	s_nop 0
	global_load_lds_dwordx4 v[208:209], off
	s_waitcnt vmcnt(8)
	s_waitcnt lgkmcnt(0)
	s_barrier
	v_mfma_f32_16x16x32_bf16 v[166:169], v[48:51], v[146:149], v[166:169]
	v_mfma_f32_16x16x32_bf16 v[162:165], v[72:75], v[146:149], v[162:165]
	v_mfma_f32_16x16x32_bf16 v[142:145], v[48:51], v[170:173], v[142:145]
	v_mfma_f32_16x16x32_bf16 v[138:141], v[72:75], v[170:173], v[138:141]
	v_mfma_f32_16x16x32_bf16 v[116:119], v[48:51], v[178:181], v[116:119]
	v_mfma_f32_16x16x32_bf16 v[112:115], v[72:75], v[178:181], v[112:115]
	v_mfma_f32_16x16x32_bf16 v[92:95], v[48:51], v[186:189], v[92:95]
	v_mfma_f32_16x16x32_bf16 v[88:91], v[72:75], v[186:189], v[88:91]
	v_mfma_f32_16x16x32_bf16 v[166:169], v[60:63], v[150:153], v[166:169]
	v_mfma_f32_16x16x32_bf16 v[162:165], v[84:87], v[150:153], v[162:165]
	v_mfma_f32_16x16x32_bf16 v[142:145], v[60:63], v[174:177], v[142:145]
	v_mfma_f32_16x16x32_bf16 v[138:141], v[84:87], v[174:177], v[138:141]
	v_mfma_f32_16x16x32_bf16 v[116:119], v[60:63], v[182:185], v[116:119]
	v_mfma_f32_16x16x32_bf16 v[112:115], v[84:87], v[182:185], v[112:115]
	v_mfma_f32_16x16x32_bf16 v[92:95], v[60:63], v[204:207], v[92:95]
	v_mfma_f32_16x16x32_bf16 v[88:91], v[84:87], v[204:207], v[88:91]
	v_mfma_f32_16x16x32_bf16 v[158:161], v[96:99], v[146:149], v[158:161]
	v_mfma_f32_16x16x32_bf16 v[130:133], v[96:99], v[170:173], v[130:133]
	v_mfma_f32_16x16x32_bf16 v[124:127], v[120:123], v[170:173], v[124:127]
	v_mfma_f32_16x16x32_bf16 v[104:107], v[96:99], v[178:181], v[104:107]
	v_mfma_f32_16x16x32_bf16 v[100:103], v[120:123], v[178:181], v[100:103]
	v_mfma_f32_16x16x32_bf16 v[80:83], v[96:99], v[186:189], v[80:83]
	v_mfma_f32_16x16x32_bf16 v[76:79], v[120:123], v[186:189], v[76:79]
	v_mfma_f32_16x16x32_bf16 v[158:161], v[108:111], v[150:153], v[158:161]
	v_mfma_f32_16x16x32_bf16 v[146:149], v[120:123], v[146:149], v[154:157]
	v_mfma_f32_16x16x32_bf16 v[130:133], v[108:111], v[174:177], v[130:133]
	v_mfma_f32_16x16x32_bf16 v[124:127], v[134:137], v[174:177], v[124:127]
	v_mfma_f32_16x16x32_bf16 v[104:107], v[108:111], v[182:185], v[104:107]
	v_mfma_f32_16x16x32_bf16 v[100:103], v[134:137], v[182:185], v[100:103]
	v_mfma_f32_16x16x32_bf16 v[80:83], v[108:111], v[204:207], v[80:83]
	v_mfma_f32_16x16x32_bf16 v[76:79], v[134:137], v[204:207], v[76:79]
	v_mfma_f32_16x16x32_bf16 v[146:149], v[134:137], v[150:153], v[146:149]
	s_barrier
	s_add_i32 s93, s93, s20
	v_lshl_add_u64 v[208:209], vcc, 0, v[128:129]
	s_mov_b32 m0, s93
	ds_read_b128 v[150:153], v231 offset:16384
	ds_read_b128 v[154:157], v231 offset:17408
	ds_read_b128 v[170:173], v231 offset:18432
	ds_read_b128 v[174:177], v231 offset:19456
	ds_read_b128 v[178:181], v231 offset:20480
	ds_read_b128 v[182:185], v231 offset:21504
	ds_read_b128 v[186:189], v231 offset:22528
	ds_read_b128 v[204:207], v231 offset:23552
	global_load_lds_dwordx4 v[208:209], off
	s_add_i32 m0, s93, 0x2000
	v_lshl_add_u64 v[210:211], vcc, 0, v[194:195]
	s_add_u32 vcc_lo, vcc_lo, s0
	s_addc_u32 vcc_hi, vcc_hi, 0
	s_add_i32 s92, s92, s20
	global_load_lds_dwordx4 v[210:211], off
	v_lshl_add_u64 v[212:213], vcc, 0, v[128:129]
	s_mov_b32 m0, s92
	v_lshl_add_u64 v[214:215], vcc, 0, v[194:195]
	global_load_lds_dwordx4 v[212:213], off
	s_add_i32 m0, s92, 0x2000
	v_lshl_add_u64 v[216:217], s[66:67], 0, v[190:191]
	global_load_lds_dwordx4 v[214:215], off
	s_mov_b32 m0, s26
	v_lshl_add_u64 v[218:219], s[66:67], 0, v[192:193]
	global_load_lds_dwordx4 v[216:217], off
	s_mov_b32 m0, s27
	s_nop 0
	global_load_lds_dwordx4 v[218:219], off
	s_waitcnt vmcnt(8)
	s_waitcnt lgkmcnt(0)
	s_barrier
; #define PG8_STAGE(bufoff, gbase, voff) do { _Pragma("unroll") for (int _i = 0; _i < 2; ++_i) \
;         __builtin_amdgcn_global_load_lds((const unsigned*)((const char*)(gbase) + (voff)[_i]), (PG8_LAS unsigned*)(lds + (bufoff) + ldsw + _i * 8192), 16, 0, 0); } while (0)
; #define PG8_LDA(dst, b, h) do { _Pragma("unroll") for (int m = 0; m < 4; ++m) _Pragma("unroll") for (int k = 0; k < 2; ++k) dst[m][k] = *(const PG8_LAS bf16x8*)(lds + PG8_SA(b, h) + aoff + m * 2048 + k * 1024); } while (0)
; #define PG8_LDB(dst, b, h) do { _Pragma("unroll") for (int n = 0; n < 2; ++n) _Pragma("unroll") for (int k = 0; k < 2; ++k) dst[n][k] = *(const PG8_LAS bf16x8*)(lds + PG8_SB(b, h) + boff + n * 2048 + k * 1024); } while (0)
; #define PG8_MMA(ai, bj, At, Bt) do { __builtin_amdgcn_s_setprio(1); _Pragma("unroll") for (int m = 0; m < 4; ++m) _Pragma("unroll") for (int n = 0; n < 2; ++n) _Pragma("unroll") for (int k = 0; k < 2; ++k) \
;         acc[ai][bj][m][n] = __builtin_amdgcn_mfma_f32_16x16x32_bf16(Bt[n][k], At[m][k], acc[ai][bj][m][n], 0, 0, 0); __builtin_amdgcn_s_setprio(0); } while (0)
; #define PG8_WAIT_V(n) asm volatile("s_waitcnt vmcnt(" #n ")" ::: "memory")
; #define PG8_WAIT_L(n) asm volatile("s_waitcnt lgkmcnt(" #n ")" ::: "memory")
; #define PG8_BAR __builtin_amdgcn_s_barrier()
; #define PG8_SCHED __builtin_amdgcn_sched_barrier(0)
; template <class Epi, class Sched, bool ALIGN_EPI = false, bool SP2 = false>
; __device__ __forceinline__ void gemm_phase(PG8_LAS unsigned char* lds, const Gemm g, const Sched& S, const Epi& E) {
;     ...
;             PG8_WAIT_V(8); PG8_WAIT_L(0); PG8_BAR; PG8_MMA(1, 0, At, B0); PG8_MMA(1, 1, At, B1); PG8_BAR; PG8_SCHED;
;             PG8_LDB(B0, 1, 0); PG8_LDB(B1, 1, 1); PG8_SCHED; PG8_LDA(At, 1, 0); PG8_STAGE(PG8_SA(0, 1), a2 + hstep, voffA);
;             PG8_WAIT_V(8); PG8_WAIT_L(0); PG8_BAR; PG8_MMA(0, 0, At, B0); PG8_MMA(0, 1, At, B1); PG8_BAR; PG8_SCHED;
	v_mfma_f32_16x16x32_bf16 v[68:71], v[48:51], v[150:153], v[68:71]
	v_mfma_f32_16x16x32_bf16 v[64:67], v[72:75], v[150:153], v[64:67]
	v_mfma_f32_16x16x32_bf16 v[44:47], v[48:51], v[170:173], v[44:47]
	v_mfma_f32_16x16x32_bf16 v[40:43], v[72:75], v[170:173], v[40:43]
	v_mfma_f32_16x16x32_bf16 v[28:31], v[48:51], v[178:181], v[28:31]
	v_mfma_f32_16x16x32_bf16 v[24:27], v[72:75], v[178:181], v[24:27]
	v_mfma_f32_16x16x32_bf16 v[12:15], v[48:51], v[186:189], v[12:15]
	v_mfma_f32_16x16x32_bf16 v[8:11], v[72:75], v[186:189], v[8:11]
	v_mfma_f32_16x16x32_bf16 v[68:71], v[60:63], v[154:157], v[68:71]
	v_mfma_f32_16x16x32_bf16 v[64:67], v[84:87], v[154:157], v[64:67]
	v_mfma_f32_16x16x32_bf16 v[44:47], v[60:63], v[174:177], v[44:47]
	v_mfma_f32_16x16x32_bf16 v[40:43], v[84:87], v[174:177], v[40:43]
	v_mfma_f32_16x16x32_bf16 v[28:31], v[60:63], v[182:185], v[28:31]
	v_mfma_f32_16x16x32_bf16 v[24:27], v[84:87], v[182:185], v[24:27]
	v_mfma_f32_16x16x32_bf16 v[12:15], v[60:63], v[204:207], v[12:15]
	v_mfma_f32_16x16x32_bf16 v[8:11], v[84:87], v[204:207], v[8:11]
	v_mfma_f32_16x16x32_bf16 v[52:55], v[120:123], v[150:153], v[52:55]
	v_mfma_f32_16x16x32_bf16 v[36:39], v[96:99], v[170:173], v[36:39]
	v_mfma_f32_16x16x32_bf16 v[32:35], v[120:123], v[170:173], v[32:35]
	v_mfma_f32_16x16x32_bf16 v[20:23], v[96:99], v[178:181], v[20:23]
	v_mfma_f32_16x16x32_bf16 v[16:19], v[120:123], v[178:181], v[16:19]
	v_mfma_f32_16x16x32_bf16 v[4:7], v[96:99], v[186:189], v[4:7]
	v_mfma_f32_16x16x32_bf16 v[0:3], v[120:123], v[186:189], v[0:3]
	v_mfma_f32_16x16x32_bf16 v[48:51], v[96:99], v[150:153], v[56:59]
	v_mfma_f32_16x16x32_bf16 v[52:55], v[134:137], v[154:157], v[52:55]
	v_mfma_f32_16x16x32_bf16 v[36:39], v[108:111], v[174:177], v[36:39]
	v_mfma_f32_16x16x32_bf16 v[32:35], v[134:137], v[174:177], v[32:35]
	v_mfma_f32_16x16x32_bf16 v[20:23], v[108:111], v[182:185], v[20:23]
	v_mfma_f32_16x16x32_bf16 v[16:19], v[134:137], v[182:185], v[16:19]
	v_mfma_f32_16x16x32_bf16 v[4:7], v[108:111], v[204:207], v[4:7]
	v_mfma_f32_16x16x32_bf16 v[0:3], v[134:137], v[204:207], v[0:3]
	v_mfma_f32_16x16x32_bf16 v[48:51], v[108:111], v[154:157], v[48:51]
	s_barrier
	s_add_i32 s92, 0, 0x18000
	s_add_i32 s93, 0, 0x1c000
	v_add_u32_e32 v84, s92, v229
	v_add_u32_e32 v134, s93, v229
	ds_read_b128 v[56:59], v84
	ds_read_b128 v[60:63], v84 offset:1024
	ds_read_b128 v[72:75], v84 offset:2048
	ds_read_b128 v[84:87], v84 offset:3072
	ds_read_b128 v[96:99], v134
	ds_read_b128 v[108:111], v134 offset:1024
	ds_read_b128 v[120:123], v134 offset:2048
	ds_read_b128 v[134:137], v134 offset:3072
	s_add_u32 s66, s66, s0
	s_addc_u32 s67, s67, 0
	s_mov_b32 m0, s18
	v_lshl_add_u64 v[220:221], s[66:67], 0, v[190:191]
	ds_read_b128 v[150:153], v231 offset:32768
	ds_read_b128 v[154:157], v231 offset:33792
	ds_read_b128 v[170:173], v231 offset:34816
	ds_read_b128 v[174:177], v231 offset:35840
	ds_read_b128 v[178:181], v231 offset:36864
	ds_read_b128 v[182:185], v231 offset:37888
	ds_read_b128 v[186:189], v231 offset:38912
	ds_read_b128 v[204:207], v231 offset:39936
	global_load_lds_dwordx4 v[220:221], off
	v_lshl_add_u64 v[220:221], s[66:67], 0, v[192:193]
	s_mov_b32 m0, s19
	s_nop 0
	global_load_lds_dwordx4 v[220:221], off
	s_waitcnt vmcnt(8)
	s_waitcnt lgkmcnt(0)
	s_barrier
	v_mfma_f32_16x16x32_bf16 v[166:169], v[56:59], v[150:153], v[166:169]
	v_mfma_f32_16x16x32_bf16 v[162:165], v[72:75], v[150:153], v[162:165]
	v_mfma_f32_16x16x32_bf16 v[142:145], v[56:59], v[170:173], v[142:145]
	v_mfma_f32_16x16x32_bf16 v[138:141], v[72:75], v[170:173], v[138:141]
	v_mfma_f32_16x16x32_bf16 v[116:119], v[56:59], v[178:181], v[116:119]
	v_mfma_f32_16x16x32_bf16 v[112:115], v[72:75], v[178:181], v[112:115]
	v_mfma_f32_16x16x32_bf16 v[92:95], v[56:59], v[186:189], v[92:95]
	v_mfma_f32_16x16x32_bf16 v[88:91], v[72:75], v[186:189], v[88:91]
	v_mfma_f32_16x16x32_bf16 v[166:169], v[60:63], v[154:157], v[166:169]
	v_mfma_f32_16x16x32_bf16 v[162:165], v[84:87], v[154:157], v[162:165]
	v_mfma_f32_16x16x32_bf16 v[142:145], v[60:63], v[174:177], v[142:145]
	v_mfma_f32_16x16x32_bf16 v[138:141], v[84:87], v[174:177], v[138:141]
	v_mfma_f32_16x16x32_bf16 v[116:119], v[60:63], v[182:185], v[116:119]
	v_mfma_f32_16x16x32_bf16 v[112:115], v[84:87], v[182:185], v[112:115]
	v_mfma_f32_16x16x32_bf16 v[92:95], v[60:63], v[204:207], v[92:95]
	v_mfma_f32_16x16x32_bf16 v[88:91], v[84:87], v[204:207], v[88:91]
	v_mfma_f32_16x16x32_bf16 v[158:161], v[96:99], v[150:153], v[158:161]
	v_mfma_f32_16x16x32_bf16 v[146:149], v[120:123], v[150:153], v[146:149]
	v_mfma_f32_16x16x32_bf16 v[130:133], v[96:99], v[170:173], v[130:133]
	v_mfma_f32_16x16x32_bf16 v[124:127], v[120:123], v[170:173], v[124:127]
	v_mfma_f32_16x16x32_bf16 v[104:107], v[96:99], v[178:181], v[104:107]
	v_mfma_f32_16x16x32_bf16 v[100:103], v[120:123], v[178:181], v[100:103]
	v_mfma_f32_16x16x32_bf16 v[80:83], v[96:99], v[186:189], v[80:83]
	v_mfma_f32_16x16x32_bf16 v[76:79], v[120:123], v[186:189], v[76:79]
	v_mfma_f32_16x16x32_bf16 v[158:161], v[108:111], v[154:157], v[158:161]
	v_mfma_f32_16x16x32_bf16 v[154:157], v[134:137], v[154:157], v[146:149]
	v_mfma_f32_16x16x32_bf16 v[130:133], v[108:111], v[174:177], v[130:133]
	v_mfma_f32_16x16x32_bf16 v[124:127], v[134:137], v[174:177], v[124:127]
	v_mfma_f32_16x16x32_bf16 v[104:107], v[108:111], v[182:185], v[104:107]
	v_mfma_f32_16x16x32_bf16 v[100:103], v[134:137], v[182:185], v[100:103]
	v_mfma_f32_16x16x32_bf16 v[80:83], v[108:111], v[204:207], v[80:83]
	v_mfma_f32_16x16x32_bf16 v[76:79], v[134:137], v[204:207], v[76:79]
	s_barrier
; #define PG8_STAGE(bufoff, gbase, voff) do { _Pragma("unroll") for (int _i = 0; _i < 2; ++_i) \
;         __builtin_amdgcn_global_load_lds((const unsigned*)((const char*)(gbase) + (voff)[_i]), (PG8_LAS unsigned*)(lds + (bufoff) + ldsw + _i * 8192), 16, 0, 0); } while (0)
; #define PG8_LDA(dst, b, h) do { _Pragma("unroll") for (int m = 0; m < 4; ++m) _Pragma("unroll") for (int k = 0; k < 2; ++k) dst[m][k] = *(const PG8_LAS bf16x8*)(lds + PG8_SA(b, h) + aoff + m * 2048 + k * 1024); } while (0)
; #define PG8_MMA(ai, bj, At, Bt) do { __builtin_amdgcn_s_setprio(1); _Pragma("unroll") for (int m = 0; m < 4; ++m) _Pragma("unroll") for (int n = 0; n < 2; ++n) _Pragma("unroll") for (int k = 0; k < 2; ++k) \
;         acc[ai][bj][m][n] = __builtin_amdgcn_mfma_f32_16x16x32_bf16(Bt[n][k], At[m][k], acc[ai][bj][m][n], 0, 0, 0); __builtin_amdgcn_s_setprio(0); } while (0)
; #define PG8_WAIT_V(n) asm volatile("s_waitcnt vmcnt(" #n ")" ::: "memory")
; #define PG8_WAIT_L(n) asm volatile("s_waitcnt lgkmcnt(" #n ")" ::: "memory")
; #define PG8_BAR __builtin_amdgcn_s_barrier()
; #define PG8_SCHED __builtin_amdgcn_sched_barrier(0)
; template <class Epi, class Sched, bool ALIGN_EPI = false, bool SP2 = false>
; __device__ __forceinline__ void gemm_phase(PG8_LAS unsigned char* lds, const Gemm g, const Sched& S, const Epi& E) {
;     ...
;             PG8_LDA(At, 1, 1); PG8_STAGE(PG8_SB(1, 0), b3, voffB); PG8_STAGE(PG8_SB(1, 1), b3 + hstep, voffB); PG8_STAGE(PG8_SA(1, 0), a3, voffA);
;             PG8_WAIT_V(8); PG8_WAIT_L(0); PG8_BAR; PG8_MMA(1, 0, At, B0); PG8_MMA(1, 1, At, B1); PG8_BAR; PG8_SCHED;
;     ...
;         if constexpr (ALIGN_EPI) { if (wr == 0) PG8_BAR; }
	s_add_i32 s66, s92, s20
	v_lshl_add_u64 v[208:209], v[208:209], 0, s[76:77]
	s_mov_b32 m0, s66
	ds_read_b128 v[146:149], v231 offset:49152
	ds_read_b128 v[150:153], v231 offset:50176
	ds_read_b128 v[170:173], v231 offset:51200
	ds_read_b128 v[174:177], v231 offset:52224
	ds_read_b128 v[178:181], v231 offset:53248
	ds_read_b128 v[182:185], v231 offset:54272
	ds_read_b128 v[186:189], v231 offset:55296
	ds_read_b128 v[204:207], v231 offset:56320
	global_load_lds_dwordx4 v[208:209], off
	v_lshl_add_u64 v[208:209], v[210:211], 0, s[76:77]
	s_add_i32 m0, s66, 0x2000
	s_add_i32 s66, s93, s20
	global_load_lds_dwordx4 v[208:209], off
	v_lshl_add_u64 v[208:209], v[212:213], 0, s[76:77]
	s_mov_b32 m0, s66
	s_nop 0
	global_load_lds_dwordx4 v[208:209], off
	v_lshl_add_u64 v[208:209], v[214:215], 0, s[76:77]
	s_add_i32 m0, s66, 0x2000
	s_nop 0
	global_load_lds_dwordx4 v[208:209], off
	v_lshl_add_u64 v[208:209], v[216:217], 0, s[76:77]
	s_mov_b32 m0, s14
	s_nop 0
	global_load_lds_dwordx4 v[208:209], off
	v_lshl_add_u64 v[208:209], v[218:219], 0, s[76:77]
	s_mov_b32 m0, s72
	s_nop 0
	global_load_lds_dwordx4 v[208:209], off
	s_waitcnt vmcnt(8)
	s_waitcnt lgkmcnt(0)
	s_barrier
	v_mfma_f32_16x16x32_bf16 v[68:71], v[56:59], v[146:149], v[68:71]
	v_mfma_f32_16x16x32_bf16 v[64:67], v[72:75], v[146:149], v[64:67]
	v_mfma_f32_16x16x32_bf16 v[44:47], v[56:59], v[170:173], v[44:47]
	v_mfma_f32_16x16x32_bf16 v[40:43], v[72:75], v[170:173], v[40:43]
	v_mfma_f32_16x16x32_bf16 v[28:31], v[56:59], v[178:181], v[28:31]
	v_mfma_f32_16x16x32_bf16 v[24:27], v[72:75], v[178:181], v[24:27]
	v_mfma_f32_16x16x32_bf16 v[12:15], v[56:59], v[186:189], v[12:15]
	v_mfma_f32_16x16x32_bf16 v[8:11], v[72:75], v[186:189], v[8:11]
	v_mfma_f32_16x16x32_bf16 v[68:71], v[60:63], v[150:153], v[68:71]
	v_mfma_f32_16x16x32_bf16 v[64:67], v[84:87], v[150:153], v[64:67]
	v_mfma_f32_16x16x32_bf16 v[44:47], v[60:63], v[174:177], v[44:47]
	v_mfma_f32_16x16x32_bf16 v[40:43], v[84:87], v[174:177], v[40:43]
	v_mfma_f32_16x16x32_bf16 v[28:31], v[60:63], v[182:185], v[28:31]
	v_mfma_f32_16x16x32_bf16 v[24:27], v[84:87], v[182:185], v[24:27]
	v_mfma_f32_16x16x32_bf16 v[12:15], v[60:63], v[204:207], v[12:15]
	v_mfma_f32_16x16x32_bf16 v[8:11], v[84:87], v[204:207], v[8:11]
	v_mfma_f32_16x16x32_bf16 v[48:51], v[96:99], v[146:149], v[48:51]
	v_mfma_f32_16x16x32_bf16 v[56:59], v[108:111], v[150:153], v[48:51]
	v_mfma_f32_16x16x32_bf16 v[48:51], v[120:123], v[146:149], v[52:55]
	v_mfma_f32_16x16x32_bf16 v[36:39], v[96:99], v[170:173], v[36:39]
	v_mfma_f32_16x16x32_bf16 v[32:35], v[120:123], v[170:173], v[32:35]
	v_mfma_f32_16x16x32_bf16 v[20:23], v[96:99], v[178:181], v[20:23]
	v_mfma_f32_16x16x32_bf16 v[16:19], v[120:123], v[178:181], v[16:19]
	v_mfma_f32_16x16x32_bf16 v[4:7], v[96:99], v[186:189], v[4:7]
	v_mfma_f32_16x16x32_bf16 v[0:3], v[120:123], v[186:189], v[0:3]
	v_mfma_f32_16x16x32_bf16 v[52:55], v[134:137], v[150:153], v[48:51]
	v_mfma_f32_16x16x32_bf16 v[36:39], v[108:111], v[174:177], v[36:39]
	v_mfma_f32_16x16x32_bf16 v[32:35], v[134:137], v[174:177], v[32:35]
	v_mfma_f32_16x16x32_bf16 v[20:23], v[108:111], v[182:185], v[20:23]
	v_mfma_f32_16x16x32_bf16 v[16:19], v[134:137], v[182:185], v[16:19]
	v_mfma_f32_16x16x32_bf16 v[4:7], v[108:111], v[204:207], v[4:7]
	v_mfma_f32_16x16x32_bf16 v[0:3], v[134:137], v[204:207], v[0:3]
	s_barrier
	s_add_u32 s13, s13, 0x100
	s_addc_u32 s91, s91, 0
	s_add_u32 s10, s10, 0x100
	s_addc_u32 s11, s11, 0
	s_cmp_ge_u32 s96, s16
	s_mov_b32 s66, s96
	s_cbranch_scc0 .LBB0_458
	s_and_b64 vcc, exec, s[60:61]
	s_cbranch_vccz .LBB0_461
	s_barrier

; #define PG8_STAGE(bufoff, gbase, voff) do { _Pragma("unroll") for (int _i = 0; _i < 2; ++_i) \
;         __builtin_amdgcn_global_load_lds((const unsigned*)((const char*)(gbase) + (voff)[_i]), (PG8_LAS unsigned*)(lds + (bufoff) + ldsw + _i * 8192), 16, 0, 0); } while (0)
; #define PG8_LDA(dst, b, h) do { _Pragma("unroll") for (int m = 0; m < 4; ++m) _Pragma("unroll") for (int k = 0; k < 2; ++k) dst[m][k] = *(const PG8_LAS bf16x8*)(lds + PG8_SA(b, h) + aoff + m * 2048 + k * 1024); } while (0)
; #define PG8_LDB(dst, b, h) do { _Pragma("unroll") for (int n = 0; n < 2; ++n) _Pragma("unroll") for (int k = 0; k < 2; ++k) dst[n][k] = *(const PG8_LAS bf16x8*)(lds + PG8_SB(b, h) + boff + n * 2048 + k * 1024); } while (0)
; #define PG8_MMA(ai, bj, At, Bt) do { __builtin_amdgcn_s_setprio(1); _Pragma("unroll") for (int m = 0; m < 4; ++m) _Pragma("unroll") for (int n = 0; n < 2; ++n) _Pragma("unroll") for (int k = 0; k < 2; ++k) \
;         acc[ai][bj][m][n] = __builtin_amdgcn_mfma_f32_16x16x32_bf16(Bt[n][k], At[m][k], acc[ai][bj][m][n], 0, 0, 0); __builtin_amdgcn_s_setprio(0); } while (0)
; #define PG8_WAIT_V(n) asm volatile("s_waitcnt vmcnt(" #n ")" ::: "memory")
; #define PG8_WAIT_L(n) asm volatile("s_waitcnt lgkmcnt(" #n ")" ::: "memory")
; #define PG8_BAR __builtin_amdgcn_s_barrier()
; #define PG8_SCHED __builtin_amdgcn_sched_barrier(0)
; template <class Epi, class Sched, bool ALIGN_EPI = false, bool SP2 = false>
; __device__ __forceinline__ void gemm_phase(PG8_LAS unsigned char* lds, const Gemm g, const Sched& S, const Epi& E) {
;     ...
;             PG8_LDB(B0, 0, 0); PG8_LDB(B1, 0, 1); PG8_SCHED; PG8_LDA(At, 0, 0); PG8_STAGE(PG8_SA(1, 1), a1 + hstep, voffA);
;             PG8_WAIT_V(8); PG8_WAIT_L(0); PG8_BAR; PG8_MMA(0, 0, At, B0); PG8_MMA(0, 1, At, B1); PG8_BAR; PG8_SCHED;
;             PG8_LDA(At, 0, 1); PG8_STAGE(PG8_SB(0, 0), b2, voffB); PG8_STAGE(PG8_SB(0, 1), b2 + hstep, voffB); PG8_STAGE(PG8_SA(0, 0), a2, voffA);
;             PG8_WAIT_V(8); PG8_WAIT_L(0); PG8_BAR; PG8_MMA(1, 0, At, B0); PG8_MMA(1, 1, At, B1); PG8_BAR; PG8_SCHED;
.LBB0_590:
	s_add_u32 s8, s0, 0xfff80080
	s_addc_u32 s9, s1, -1
	s_add_i32 s61, 0, 0x10000
	s_cmp_eq_u32 s60, 28
	s_cselect_b32 s29, s14, s9
	s_cselect_b32 s28, s26, s8
	v_add_u32_e32 v128, s61, v187
	s_cselect_b32 s9, s27, s35
	s_cselect_b32 s8, s31, s34
	s_add_i32 s65, 0, 0x14000
	ds_read_b128 v[56:59], v128
	ds_read_b128 v[138:141], v128 offset:1024
	ds_read_b128 v[142:145], v128 offset:2048
	ds_read_b128 v[160:163], v128 offset:3072
	v_add_u32_e32 v128, s65, v187
	ds_read_b128 v[164:167], v128
	ds_read_b128 v[176:179], v128 offset:1024
	ds_read_b128 v[180:183], v128 offset:2048
	ds_read_b128 v[190:193], v128 offset:3072
	v_lshl_add_u64 v[168:169], s[0:1], 0, v[158:159]
	s_add_i32 m0, s5, 0xc000
	ds_read_b128 v[194:197], v189
	ds_read_b128 v[198:201], v189 offset:1024
	ds_read_b128 v[202:205], v189 offset:2048
	ds_read_b128 v[206:209], v189 offset:3072
	ds_read_b128 v[210:213], v189 offset:4096
	ds_read_b128 v[214:217], v189 offset:5120
	ds_read_b128 v[218:221], v189 offset:6144
	ds_read_b128 v[222:225], v189 offset:7168
	global_load_lds_dwordx4 v[168:169], off
	v_lshl_add_u64 v[168:169], s[0:1], 0, v[156:157]
	s_add_i32 m0, s5, 0xe000
	s_nop 0
	global_load_lds_dwordx4 v[168:169], off
	s_waitcnt vmcnt(8)
	s_waitcnt lgkmcnt(0)
	s_barrier
	v_mfma_f32_16x16x32_bf16 v[134:137], v[56:59], v[194:197], v[134:137]
	v_mfma_f32_16x16x32_bf16 v[124:127], v[142:145], v[194:197], v[124:127]
	v_mfma_f32_16x16x32_bf16 v[116:119], v[56:59], v[202:205], v[116:119]
	v_mfma_f32_16x16x32_bf16 v[104:107], v[142:145], v[202:205], v[104:107]
	v_mfma_f32_16x16x32_bf16 v[96:99], v[56:59], v[210:213], v[96:99]
	v_mfma_f32_16x16x32_bf16 v[88:91], v[142:145], v[210:213], v[88:91]
	v_mfma_f32_16x16x32_bf16 v[80:83], v[56:59], v[218:221], v[80:83]
	v_mfma_f32_16x16x32_bf16 v[72:75], v[142:145], v[218:221], v[72:75]
	v_mfma_f32_16x16x32_bf16 v[134:137], v[138:141], v[198:201], v[134:137]
	v_mfma_f32_16x16x32_bf16 v[124:127], v[160:163], v[198:201], v[124:127]
	v_mfma_f32_16x16x32_bf16 v[116:119], v[138:141], v[206:209], v[116:119]
	v_mfma_f32_16x16x32_bf16 v[104:107], v[160:163], v[206:209], v[104:107]
	v_mfma_f32_16x16x32_bf16 v[96:99], v[138:141], v[214:217], v[96:99]
	v_mfma_f32_16x16x32_bf16 v[88:91], v[160:163], v[214:217], v[88:91]
	v_mfma_f32_16x16x32_bf16 v[80:83], v[138:141], v[222:225], v[80:83]
	v_mfma_f32_16x16x32_bf16 v[72:75], v[160:163], v[222:225], v[72:75]
	v_mfma_f32_16x16x32_bf16 v[130:133], v[164:167], v[194:197], v[130:133]
	v_mfma_f32_16x16x32_bf16 v[120:123], v[180:183], v[194:197], v[120:123]
	v_mfma_f32_16x16x32_bf16 v[112:115], v[164:167], v[202:205], v[112:115]
	v_mfma_f32_16x16x32_bf16 v[100:103], v[180:183], v[202:205], v[100:103]
	v_mfma_f32_16x16x32_bf16 v[92:95], v[164:167], v[210:213], v[92:95]
	v_mfma_f32_16x16x32_bf16 v[84:87], v[180:183], v[210:213], v[84:87]
	v_mfma_f32_16x16x32_bf16 v[76:79], v[164:167], v[218:221], v[76:79]
	v_mfma_f32_16x16x32_bf16 v[68:71], v[180:183], v[218:221], v[68:71]
	v_mfma_f32_16x16x32_bf16 v[130:133], v[176:179], v[198:201], v[130:133]
	v_mfma_f32_16x16x32_bf16 v[120:123], v[190:193], v[198:201], v[120:123]
	v_mfma_f32_16x16x32_bf16 v[112:115], v[176:179], v[206:209], v[112:115]
	v_mfma_f32_16x16x32_bf16 v[100:103], v[190:193], v[206:209], v[100:103]
	v_mfma_f32_16x16x32_bf16 v[92:95], v[176:179], v[214:217], v[92:95]
	v_mfma_f32_16x16x32_bf16 v[84:87], v[190:193], v[214:217], v[84:87]
	v_mfma_f32_16x16x32_bf16 v[76:79], v[176:179], v[222:225], v[76:79]
	v_mfma_f32_16x16x32_bf16 v[68:71], v[190:193], v[222:225], v[68:71]
	s_barrier
	s_add_i32 s61, s61, s20
	v_lshl_add_u64 v[168:169], s[8:9], 0, v[150:151]
	s_mov_b32 m0, s61
	ds_read_b128 v[194:197], v189 offset:16384
	ds_read_b128 v[198:201], v189 offset:17408
	ds_read_b128 v[202:205], v189 offset:18432
	ds_read_b128 v[206:209], v189 offset:19456
	ds_read_b128 v[210:213], v189 offset:20480
	ds_read_b128 v[214:217], v189 offset:21504
	ds_read_b128 v[218:221], v189 offset:22528
	ds_read_b128 v[222:225], v189 offset:23552
	global_load_lds_dwordx4 v[168:169], off
	s_add_i32 m0, s61, 0x2000
	s_add_u32 s66, s8, 0x80000
	v_lshl_add_u64 v[184:185], s[8:9], 0, v[146:147]
	s_addc_u32 s67, s9, 0
	s_add_i32 s61, s65, s20
	global_load_lds_dwordx4 v[184:185], off
	v_lshl_add_u64 v[226:227], s[66:67], 0, v[150:151]
	s_mov_b32 m0, s61
	v_lshl_add_u64 v[228:229], s[28:29], 0, v[148:149]
	global_load_lds_dwordx4 v[226:227], off
	v_lshl_add_u64 v[226:227], s[66:67], 0, v[146:147]
	s_add_i32 m0, s61, 0x2000
	s_nop 0
	global_load_lds_dwordx4 v[226:227], off
	v_lshl_add_u64 v[226:227], s[28:29], 0, v[152:153]
	s_mov_b32 m0, s5
	s_nop 0
	global_load_lds_dwordx4 v[226:227], off
	s_mov_b32 m0, s15
	s_nop 0
	global_load_lds_dwordx4 v[228:229], off
	s_waitcnt vmcnt(8)
	s_waitcnt lgkmcnt(0)
	s_barrier
; #define PG8_STAGE(bufoff, gbase, voff) do { _Pragma("unroll") for (int _i = 0; _i < 2; ++_i) \
;         __builtin_amdgcn_global_load_lds((const unsigned*)((const char*)(gbase) + (voff)[_i]), (PG8_LAS unsigned*)(lds + (bufoff) + ldsw + _i * 8192), 16, 0, 0); } while (0)
; #define PG8_LDA(dst, b, h) do { _Pragma("unroll") for (int m = 0; m < 4; ++m) _Pragma("unroll") for (int k = 0; k < 2; ++k) dst[m][k] = *(const PG8_LAS bf16x8*)(lds + PG8_SA(b, h) + aoff + m * 2048 + k * 1024); } while (0)
; #define PG8_LDB(dst, b, h) do { _Pragma("unroll") for (int n = 0; n < 2; ++n) _Pragma("unroll") for (int k = 0; k < 2; ++k) dst[n][k] = *(const PG8_LAS bf16x8*)(lds + PG8_SB(b, h) + boff + n * 2048 + k * 1024); } while (0)
; #define PG8_MMA(ai, bj, At, Bt) do { __builtin_amdgcn_s_setprio(1); _Pragma("unroll") for (int m = 0; m < 4; ++m) _Pragma("unroll") for (int n = 0; n < 2; ++n) _Pragma("unroll") for (int k = 0; k < 2; ++k) \
;         acc[ai][bj][m][n] = __builtin_amdgcn_mfma_f32_16x16x32_bf16(Bt[n][k], At[m][k], acc[ai][bj][m][n], 0, 0, 0); __builtin_amdgcn_s_setprio(0); } while (0)
; #define PG8_WAIT_V(n) asm volatile("s_waitcnt vmcnt(" #n ")" ::: "memory")
; #define PG8_WAIT_L(n) asm volatile("s_waitcnt lgkmcnt(" #n ")" ::: "memory")
; #define PG8_BAR __builtin_amdgcn_s_barrier()
; #define PG8_SCHED __builtin_amdgcn_sched_barrier(0)
; template <class Epi, class Sched, bool ALIGN_EPI = false, bool SP2 = false>
; __device__ __forceinline__ void gemm_phase(PG8_LAS unsigned char* lds, const Gemm g, const Sched& S, const Epi& E) {
;     ...
;             PG8_WAIT_V(8); PG8_WAIT_L(0); PG8_BAR; PG8_MMA(1, 0, At, B0); PG8_MMA(1, 1, At, B1); PG8_BAR; PG8_SCHED;
;             PG8_LDB(B0, 1, 0); PG8_LDB(B1, 1, 1); PG8_SCHED; PG8_LDA(At, 1, 0); PG8_STAGE(PG8_SA(0, 1), a2 + hstep, voffA);
;             PG8_WAIT_V(8); PG8_WAIT_L(0); PG8_BAR; PG8_MMA(0, 0, At, B0); PG8_MMA(0, 1, At, B1); PG8_BAR; PG8_SCHED;
	v_mfma_f32_16x16x32_bf16 v[64:67], v[56:59], v[194:197], v[64:67]
	v_mfma_f32_16x16x32_bf16 v[52:55], v[142:145], v[194:197], v[52:55]
	v_mfma_f32_16x16x32_bf16 v[44:47], v[56:59], v[202:205], v[44:47]
	v_mfma_f32_16x16x32_bf16 v[36:39], v[142:145], v[202:205], v[36:39]
	v_mfma_f32_16x16x32_bf16 v[28:31], v[56:59], v[210:213], v[28:31]
	v_mfma_f32_16x16x32_bf16 v[20:23], v[142:145], v[210:213], v[20:23]
	v_mfma_f32_16x16x32_bf16 v[12:15], v[56:59], v[218:221], v[12:15]
	v_mfma_f32_16x16x32_bf16 v[4:7], v[142:145], v[218:221], v[4:7]
	v_mfma_f32_16x16x32_bf16 v[64:67], v[138:141], v[198:201], v[64:67]
	v_mfma_f32_16x16x32_bf16 v[52:55], v[160:163], v[198:201], v[52:55]
	v_mfma_f32_16x16x32_bf16 v[44:47], v[138:141], v[206:209], v[44:47]
	v_mfma_f32_16x16x32_bf16 v[36:39], v[160:163], v[206:209], v[36:39]
	v_mfma_f32_16x16x32_bf16 v[28:31], v[138:141], v[214:217], v[28:31]
	v_mfma_f32_16x16x32_bf16 v[20:23], v[160:163], v[214:217], v[20:23]
	v_mfma_f32_16x16x32_bf16 v[12:15], v[138:141], v[222:225], v[12:15]
	v_mfma_f32_16x16x32_bf16 v[4:7], v[160:163], v[222:225], v[4:7]
	v_mfma_f32_16x16x32_bf16 v[48:51], v[180:183], v[194:197], v[48:51]
	v_mfma_f32_16x16x32_bf16 v[40:43], v[164:167], v[202:205], v[40:43]
	v_mfma_f32_16x16x32_bf16 v[32:35], v[180:183], v[202:205], v[32:35]
	v_mfma_f32_16x16x32_bf16 v[24:27], v[164:167], v[210:213], v[24:27]
	v_mfma_f32_16x16x32_bf16 v[16:19], v[180:183], v[210:213], v[16:19]
	v_mfma_f32_16x16x32_bf16 v[8:11], v[164:167], v[218:221], v[8:11]
	v_mfma_f32_16x16x32_bf16 v[0:3], v[180:183], v[218:221], v[0:3]
	v_mfma_f32_16x16x32_bf16 v[56:59], v[164:167], v[194:197], v[60:63]
	v_mfma_f32_16x16x32_bf16 v[48:51], v[190:193], v[198:201], v[48:51]
	v_mfma_f32_16x16x32_bf16 v[40:43], v[176:179], v[206:209], v[40:43]
	v_mfma_f32_16x16x32_bf16 v[32:35], v[190:193], v[206:209], v[32:35]
	v_mfma_f32_16x16x32_bf16 v[24:27], v[176:179], v[214:217], v[24:27]
	v_mfma_f32_16x16x32_bf16 v[16:19], v[190:193], v[214:217], v[16:19]
	v_mfma_f32_16x16x32_bf16 v[8:11], v[176:179], v[222:225], v[8:11]
	v_mfma_f32_16x16x32_bf16 v[0:3], v[190:193], v[222:225], v[0:3]
	v_mfma_f32_16x16x32_bf16 v[56:59], v[176:179], v[198:201], v[56:59]
	s_barrier
	s_add_i32 s61, 0, 0x18000
	v_add_u32_e32 v128, s61, v187
	s_add_i32 s65, 0, 0x1c000
	ds_read_b128 v[60:63], v128
	ds_read_b128 v[138:141], v128 offset:1024
	ds_read_b128 v[142:145], v128 offset:2048
	ds_read_b128 v[160:163], v128 offset:3072
	v_add_u32_e32 v128, s65, v187
	ds_read_b128 v[164:167], v128
	ds_read_b128 v[176:179], v128 offset:1024
	ds_read_b128 v[180:183], v128 offset:2048
	ds_read_b128 v[190:193], v128 offset:3072
	s_add_u32 s28, s28, 0x80000
	s_addc_u32 s29, s29, 0
	s_mov_b32 m0, s16
	v_lshl_add_u64 v[230:231], s[28:29], 0, v[152:153]
	ds_read_b128 v[194:197], v189 offset:32768
	ds_read_b128 v[198:201], v189 offset:33792
	ds_read_b128 v[202:205], v189 offset:34816
	ds_read_b128 v[206:209], v189 offset:35840
	ds_read_b128 v[210:213], v189 offset:36864
	ds_read_b128 v[214:217], v189 offset:37888
	ds_read_b128 v[218:221], v189 offset:38912
	ds_read_b128 v[222:225], v189 offset:39936
	global_load_lds_dwordx4 v[230:231], off
	v_lshl_add_u64 v[230:231], s[28:29], 0, v[148:149]
	s_mov_b32 m0, s19
	s_nop 0
	global_load_lds_dwordx4 v[230:231], off
	s_waitcnt vmcnt(8)
	s_waitcnt lgkmcnt(0)
	s_barrier
	v_mfma_f32_16x16x32_bf16 v[134:137], v[60:63], v[194:197], v[134:137]
	v_mfma_f32_16x16x32_bf16 v[124:127], v[142:145], v[194:197], v[124:127]
	v_mfma_f32_16x16x32_bf16 v[116:119], v[60:63], v[202:205], v[116:119]
	v_mfma_f32_16x16x32_bf16 v[104:107], v[142:145], v[202:205], v[104:107]
	v_mfma_f32_16x16x32_bf16 v[96:99], v[60:63], v[210:213], v[96:99]
	v_mfma_f32_16x16x32_bf16 v[88:91], v[142:145], v[210:213], v[88:91]
	v_mfma_f32_16x16x32_bf16 v[80:83], v[60:63], v[218:221], v[80:83]
	v_mfma_f32_16x16x32_bf16 v[72:75], v[142:145], v[218:221], v[72:75]
	v_mfma_f32_16x16x32_bf16 v[134:137], v[138:141], v[198:201], v[134:137]
	v_mfma_f32_16x16x32_bf16 v[124:127], v[160:163], v[198:201], v[124:127]
	v_mfma_f32_16x16x32_bf16 v[116:119], v[138:141], v[206:209], v[116:119]
	v_mfma_f32_16x16x32_bf16 v[104:107], v[160:163], v[206:209], v[104:107]
	v_mfma_f32_16x16x32_bf16 v[96:99], v[138:141], v[214:217], v[96:99]
	v_mfma_f32_16x16x32_bf16 v[88:91], v[160:163], v[214:217], v[88:91]
	v_mfma_f32_16x16x32_bf16 v[80:83], v[138:141], v[222:225], v[80:83]
	v_mfma_f32_16x16x32_bf16 v[72:75], v[160:163], v[222:225], v[72:75]
	v_mfma_f32_16x16x32_bf16 v[130:133], v[164:167], v[194:197], v[130:133]
	v_mfma_f32_16x16x32_bf16 v[120:123], v[180:183], v[194:197], v[120:123]
	v_mfma_f32_16x16x32_bf16 v[112:115], v[164:167], v[202:205], v[112:115]
	v_mfma_f32_16x16x32_bf16 v[100:103], v[180:183], v[202:205], v[100:103]
	v_mfma_f32_16x16x32_bf16 v[92:95], v[164:167], v[210:213], v[92:95]
	v_mfma_f32_16x16x32_bf16 v[84:87], v[180:183], v[210:213], v[84:87]
	v_mfma_f32_16x16x32_bf16 v[76:79], v[164:167], v[218:221], v[76:79]
	v_mfma_f32_16x16x32_bf16 v[68:71], v[180:183], v[218:221], v[68:71]
	v_mfma_f32_16x16x32_bf16 v[130:133], v[176:179], v[198:201], v[130:133]
	v_mfma_f32_16x16x32_bf16 v[120:123], v[190:193], v[198:201], v[120:123]
	v_mfma_f32_16x16x32_bf16 v[112:115], v[176:179], v[206:209], v[112:115]
	v_mfma_f32_16x16x32_bf16 v[100:103], v[190:193], v[206:209], v[100:103]
	v_mfma_f32_16x16x32_bf16 v[92:95], v[176:179], v[214:217], v[92:95]
	v_mfma_f32_16x16x32_bf16 v[84:87], v[190:193], v[214:217], v[84:87]
	v_mfma_f32_16x16x32_bf16 v[76:79], v[176:179], v[222:225], v[76:79]
	v_mfma_f32_16x16x32_bf16 v[68:71], v[190:193], v[222:225], v[68:71]
	s_barrier
; #define PG8_STAGE(bufoff, gbase, voff) do { _Pragma("unroll") for (int _i = 0; _i < 2; ++_i) \
;         __builtin_amdgcn_global_load_lds((const unsigned*)((const char*)(gbase) + (voff)[_i]), (PG8_LAS unsigned*)(lds + (bufoff) + ldsw + _i * 8192), 16, 0, 0); } while (0)
; #define PG8_LDA(dst, b, h) do { _Pragma("unroll") for (int m = 0; m < 4; ++m) _Pragma("unroll") for (int k = 0; k < 2; ++k) dst[m][k] = *(const PG8_LAS bf16x8*)(lds + PG8_SA(b, h) + aoff + m * 2048 + k * 1024); } while (0)
; #define PG8_MMA(ai, bj, At, Bt) do { __builtin_amdgcn_s_setprio(1); _Pragma("unroll") for (int m = 0; m < 4; ++m) _Pragma("unroll") for (int n = 0; n < 2; ++n) _Pragma("unroll") for (int k = 0; k < 2; ++k) \
;         acc[ai][bj][m][n] = __builtin_amdgcn_mfma_f32_16x16x32_bf16(Bt[n][k], At[m][k], acc[ai][bj][m][n], 0, 0, 0); __builtin_amdgcn_s_setprio(0); } while (0)
; #define PG8_WAIT_V(n) asm volatile("s_waitcnt vmcnt(" #n ")" ::: "memory")
; #define PG8_WAIT_L(n) asm volatile("s_waitcnt lgkmcnt(" #n ")" ::: "memory")
; #define PG8_BAR __builtin_amdgcn_s_barrier()
; #define PG8_SCHED __builtin_amdgcn_sched_barrier(0)
; template <class Epi, class Sched, bool ALIGN_EPI = false, bool SP2 = false>
; __device__ __forceinline__ void gemm_phase(PG8_LAS unsigned char* lds, const Gemm g, const Sched& S, const Epi& E) {
;     ...
;             PG8_LDA(At, 1, 1); PG8_STAGE(PG8_SB(1, 0), b3, voffB); PG8_STAGE(PG8_SB(1, 1), b3 + hstep, voffB); PG8_STAGE(PG8_SA(1, 0), a3, voffA);
;             PG8_WAIT_V(8); PG8_WAIT_L(0); PG8_BAR; PG8_MMA(1, 0, At, B0); PG8_MMA(1, 1, At, B1); PG8_BAR; PG8_SCHED;
;     ...
;         if constexpr (ALIGN_EPI) { if (wr == 0) PG8_BAR; }
	s_add_i32 s28, s61, s20
	v_lshl_add_u64 v[168:169], v[168:169], 0, s[76:77]
	s_mov_b32 m0, s28
	ds_read_b128 v[194:197], v189 offset:49152
	ds_read_b128 v[198:201], v189 offset:50176
	ds_read_b128 v[202:205], v189 offset:51200
	ds_read_b128 v[206:209], v189 offset:52224
	ds_read_b128 v[210:213], v189 offset:53248
	ds_read_b128 v[214:217], v189 offset:54272
	ds_read_b128 v[218:221], v189 offset:55296
	ds_read_b128 v[222:225], v189 offset:56320
	global_load_lds_dwordx4 v[168:169], off
	s_add_i32 m0, s28, 0x2000
	s_add_u32 s8, s8, 0x80080
	v_lshl_add_u64 v[168:169], v[184:185], 0, s[76:77]
	s_addc_u32 s9, s9, 0
	s_add_i32 s28, s65, s20
	global_load_lds_dwordx4 v[168:169], off
	v_lshl_add_u64 v[168:169], s[8:9], 0, v[150:151]
	s_mov_b32 m0, s28
	s_nop 0
	global_load_lds_dwordx4 v[168:169], off
	v_lshl_add_u64 v[168:169], s[8:9], 0, v[146:147]
	s_add_i32 m0, s28, 0x2000
	s_nop 0
	global_load_lds_dwordx4 v[168:169], off
	v_lshl_add_u64 v[168:169], v[226:227], 0, s[76:77]
	s_mov_b32 m0, s21
	s_nop 0
	global_load_lds_dwordx4 v[168:169], off
	v_lshl_add_u64 v[168:169], v[228:229], 0, s[76:77]
	s_mov_b32 m0, s22
	s_nop 0
	global_load_lds_dwordx4 v[168:169], off
	s_waitcnt vmcnt(8)
	s_waitcnt lgkmcnt(0)
	s_barrier
	v_mfma_f32_16x16x32_bf16 v[64:67], v[60:63], v[194:197], v[64:67]
	v_mfma_f32_16x16x32_bf16 v[52:55], v[142:145], v[194:197], v[52:55]
	v_mfma_f32_16x16x32_bf16 v[44:47], v[60:63], v[202:205], v[44:47]
	v_mfma_f32_16x16x32_bf16 v[36:39], v[142:145], v[202:205], v[36:39]
	v_mfma_f32_16x16x32_bf16 v[28:31], v[60:63], v[210:213], v[28:31]
	v_mfma_f32_16x16x32_bf16 v[20:23], v[142:145], v[210:213], v[20:23]
	v_mfma_f32_16x16x32_bf16 v[12:15], v[60:63], v[218:221], v[12:15]
	v_mfma_f32_16x16x32_bf16 v[4:7], v[142:145], v[218:221], v[4:7]
	v_mfma_f32_16x16x32_bf16 v[64:67], v[138:141], v[198:201], v[64:67]
	v_mfma_f32_16x16x32_bf16 v[52:55], v[160:163], v[198:201], v[52:55]
	v_mfma_f32_16x16x32_bf16 v[44:47], v[138:141], v[206:209], v[44:47]
	v_mfma_f32_16x16x32_bf16 v[36:39], v[160:163], v[206:209], v[36:39]
	v_mfma_f32_16x16x32_bf16 v[28:31], v[138:141], v[214:217], v[28:31]
	v_mfma_f32_16x16x32_bf16 v[20:23], v[160:163], v[214:217], v[20:23]
	v_mfma_f32_16x16x32_bf16 v[12:15], v[138:141], v[222:225], v[12:15]
	v_mfma_f32_16x16x32_bf16 v[4:7], v[160:163], v[222:225], v[4:7]
	v_mfma_f32_16x16x32_bf16 v[56:59], v[164:167], v[194:197], v[56:59]
	v_mfma_f32_16x16x32_bf16 v[48:51], v[180:183], v[194:197], v[48:51]
	v_mfma_f32_16x16x32_bf16 v[40:43], v[164:167], v[202:205], v[40:43]
	v_mfma_f32_16x16x32_bf16 v[32:35], v[180:183], v[202:205], v[32:35]
	v_mfma_f32_16x16x32_bf16 v[24:27], v[164:167], v[210:213], v[24:27]
	v_mfma_f32_16x16x32_bf16 v[16:19], v[180:183], v[210:213], v[16:19]
	v_mfma_f32_16x16x32_bf16 v[8:11], v[164:167], v[218:221], v[8:11]
	v_mfma_f32_16x16x32_bf16 v[0:3], v[180:183], v[218:221], v[0:3]
	v_mfma_f32_16x16x32_bf16 v[60:63], v[176:179], v[198:201], v[56:59]
	v_mfma_f32_16x16x32_bf16 v[48:51], v[190:193], v[198:201], v[48:51]
	v_mfma_f32_16x16x32_bf16 v[40:43], v[176:179], v[206:209], v[40:43]
	v_mfma_f32_16x16x32_bf16 v[32:35], v[190:193], v[206:209], v[32:35]
	v_mfma_f32_16x16x32_bf16 v[24:27], v[176:179], v[214:217], v[24:27]
	v_mfma_f32_16x16x32_bf16 v[16:19], v[190:193], v[214:217], v[16:19]
	v_mfma_f32_16x16x32_bf16 v[8:11], v[176:179], v[222:225], v[8:11]
	v_mfma_f32_16x16x32_bf16 v[0:3], v[190:193], v[222:225], v[0:3]
	s_barrier
	s_add_i32 s60, s60, 2
	s_add_u32 s34, s34, 0x100
	s_addc_u32 s35, s35, 0
	s_add_u32 s0, s0, 0x100
	s_addc_u32 s1, s1, 0
	s_cmp_gt_u32 s60, 29
	s_cbranch_scc0 .LBB0_590
	s_and_b64 vcc, exec, s[12:13]
	s_cbranch_vccz .LBB0_593
	s_barrier

; #define PG8_STAGE(bufoff, gbase, voff) do { _Pragma("unroll") for (int _i = 0; _i < 2; ++_i) \
;         __builtin_amdgcn_global_load_lds((const unsigned*)((const char*)(gbase) + (voff)[_i]), (PG8_LAS unsigned*)(lds + (bufoff) + ldsw + _i * 8192), 16, 0, 0); } while (0)
; #define PG8_LDA(dst, b, h) do { _Pragma("unroll") for (int m = 0; m < 4; ++m) _Pragma("unroll") for (int k = 0; k < 2; ++k) dst[m][k] = *(const PG8_LAS bf16x8*)(lds + PG8_SA(b, h) + aoff + m * 2048 + k * 1024); } while (0)
; #define PG8_LDB(dst, b, h) do { _Pragma("unroll") for (int n = 0; n < 2; ++n) _Pragma("unroll") for (int k = 0; k < 2; ++k) dst[n][k] = *(const PG8_LAS bf16x8*)(lds + PG8_SB(b, h) + boff + n * 2048 + k * 1024); } while (0)
; #define PG8_MMA(ai, bj, At, Bt) do { __builtin_amdgcn_s_setprio(1); _Pragma("unroll") for (int m = 0; m < 4; ++m) _Pragma("unroll") for (int n = 0; n < 2; ++n) _Pragma("unroll") for (int k = 0; k < 2; ++k) \
;         acc[ai][bj][m][n] = __builtin_amdgcn_mfma_f32_16x16x32_bf16(Bt[n][k], At[m][k], acc[ai][bj][m][n], 0, 0, 0); __builtin_amdgcn_s_setprio(0); } while (0)
; #define PG8_WAIT_V(n) asm volatile("s_waitcnt vmcnt(" #n ")" ::: "memory")
; #define PG8_WAIT_L(n) asm volatile("s_waitcnt lgkmcnt(" #n ")" ::: "memory")
; #define PG8_BAR __builtin_amdgcn_s_barrier()
; #define PG8_SCHED __builtin_amdgcn_sched_barrier(0)
; template <class Epi, class Sched, bool ALIGN_EPI = false, bool SP2 = false>
; __device__ __forceinline__ void gemm_phase(PG8_LAS unsigned char* lds, const Gemm g, const Sched& S, const Epi& E) {
;     ...
;             PG8_LDB(B0, 0, 0); PG8_LDB(B1, 0, 1); PG8_SCHED; PG8_LDA(At, 0, 0); PG8_STAGE(PG8_SA(1, 1), a1 + hstep, voffA);
;             PG8_WAIT_V(8); PG8_WAIT_L(0); PG8_BAR; PG8_MMA(0, 0, At, B0); PG8_MMA(0, 1, At, B1); PG8_BAR; PG8_SCHED;
;             PG8_LDA(At, 0, 1); PG8_STAGE(PG8_SB(0, 0), b2, voffB); PG8_STAGE(PG8_SB(0, 1), b2 + hstep, voffB); PG8_STAGE(PG8_SA(0, 0), a2, voffA);
;             PG8_WAIT_V(8); PG8_WAIT_L(0); PG8_BAR; PG8_MMA(1, 0, At, B0); PG8_MMA(1, 1, At, B1); PG8_BAR; PG8_SCHED;
.LBB0_645:
	s_add_u32 s10, s24, s8
	s_addc_u32 s11, s25, s9
	s_add_u32 s10, s10, 0xc00100
	s_addc_u32 s11, s11, 0
	s_add_u32 s27, s22, s8
	s_addc_u32 s28, s23, s9
	s_add_i32 s29, 0, 0x10000
	s_cmpk_eq_i32 s8, 0xf00
	s_cselect_b32 s13, s7, s11
	s_cselect_b32 s12, s6, s10
	s_cselect_b32 s11, s5, s28
	s_cselect_b32 s10, s4, s27
	s_add_i32 s27, 0, 0x14000
	v_add_u32_e32 v152, s29, v138
	v_add_u32_e32 v168, s27, v138
	ds_read_b128 v[140:143], v152
	ds_read_b128 v[144:147], v152 offset:1024
	ds_read_b128 v[148:151], v152 offset:2048
	ds_read_b128 v[152:155], v152 offset:3072
	ds_read_b128 v[156:159], v168
	ds_read_b128 v[160:163], v168 offset:1024
	ds_read_b128 v[164:167], v168 offset:2048
	ds_read_b128 v[168:171], v168 offset:3072
	v_lshl_add_u64 v[204:205], v[134:135], 0, s[8:9]
	s_add_i32 m0, s15, 0xc000
	ds_read_b128 v[172:175], v139
	ds_read_b128 v[176:179], v139 offset:1024
	ds_read_b128 v[180:183], v139 offset:2048
	ds_read_b128 v[184:187], v139 offset:3072
	ds_read_b128 v[188:191], v139 offset:4096
	ds_read_b128 v[192:195], v139 offset:5120
	ds_read_b128 v[196:199], v139 offset:6144
	ds_read_b128 v[200:203], v139 offset:7168
	global_load_lds_dwordx4 v[204:205], off
	v_lshl_add_u64 v[204:205], v[132:133], 0, s[8:9]
	s_add_i32 m0, s15, 0xe000
	s_nop 0
	global_load_lds_dwordx4 v[204:205], off
	s_waitcnt vmcnt(8)
	s_waitcnt lgkmcnt(0)
	s_barrier
	v_mfma_f32_16x16x32_bf16 v[124:127], v[140:143], v[172:175], v[124:127]
	v_mfma_f32_16x16x32_bf16 v[120:123], v[148:151], v[172:175], v[120:123]
	v_mfma_f32_16x16x32_bf16 v[116:119], v[140:143], v[180:183], v[116:119]
	v_mfma_f32_16x16x32_bf16 v[112:115], v[148:151], v[180:183], v[112:115]
	v_mfma_f32_16x16x32_bf16 v[104:107], v[140:143], v[188:191], v[104:107]
	v_mfma_f32_16x16x32_bf16 v[96:99], v[148:151], v[188:191], v[96:99]
	v_mfma_f32_16x16x32_bf16 v[88:91], v[140:143], v[196:199], v[88:91]
	v_mfma_f32_16x16x32_bf16 v[80:83], v[148:151], v[196:199], v[80:83]
	v_mfma_f32_16x16x32_bf16 v[124:127], v[144:147], v[176:179], v[124:127]
	v_mfma_f32_16x16x32_bf16 v[120:123], v[152:155], v[176:179], v[120:123]
	v_mfma_f32_16x16x32_bf16 v[116:119], v[144:147], v[184:187], v[116:119]
	v_mfma_f32_16x16x32_bf16 v[112:115], v[152:155], v[184:187], v[112:115]
	v_mfma_f32_16x16x32_bf16 v[104:107], v[144:147], v[192:195], v[104:107]
	v_mfma_f32_16x16x32_bf16 v[96:99], v[152:155], v[192:195], v[96:99]
	v_mfma_f32_16x16x32_bf16 v[88:91], v[144:147], v[200:203], v[88:91]
	v_mfma_f32_16x16x32_bf16 v[80:83], v[152:155], v[200:203], v[80:83]
	v_mfma_f32_16x16x32_bf16 v[108:111], v[156:159], v[172:175], v[108:111]
	v_mfma_f32_16x16x32_bf16 v[100:103], v[164:167], v[172:175], v[100:103]
	v_mfma_f32_16x16x32_bf16 v[92:95], v[156:159], v[180:183], v[92:95]
	v_mfma_f32_16x16x32_bf16 v[84:87], v[164:167], v[180:183], v[84:87]
	v_mfma_f32_16x16x32_bf16 v[76:79], v[156:159], v[188:191], v[76:79]
	v_mfma_f32_16x16x32_bf16 v[72:75], v[164:167], v[188:191], v[72:75]
	v_mfma_f32_16x16x32_bf16 v[68:71], v[156:159], v[196:199], v[68:71]
	v_mfma_f32_16x16x32_bf16 v[64:67], v[164:167], v[196:199], v[64:67]
	v_mfma_f32_16x16x32_bf16 v[108:111], v[160:163], v[176:179], v[108:111]
	v_mfma_f32_16x16x32_bf16 v[100:103], v[168:171], v[176:179], v[100:103]
	v_mfma_f32_16x16x32_bf16 v[92:95], v[160:163], v[184:187], v[92:95]
	v_mfma_f32_16x16x32_bf16 v[84:87], v[168:171], v[184:187], v[84:87]
	v_mfma_f32_16x16x32_bf16 v[76:79], v[160:163], v[192:195], v[76:79]
	v_mfma_f32_16x16x32_bf16 v[72:75], v[168:171], v[192:195], v[72:75]
	v_mfma_f32_16x16x32_bf16 v[68:71], v[160:163], v[200:203], v[68:71]
	v_mfma_f32_16x16x32_bf16 v[64:67], v[168:171], v[200:203], v[64:67]
	s_barrier
	s_add_i32 s28, s29, s14
	v_lshl_add_u64 v[204:205], s[10:11], 0, v[128:129]
	s_mov_b32 m0, s28
	ds_read_b128 v[172:175], v139 offset:16384
	ds_read_b128 v[176:179], v139 offset:17408
	ds_read_b128 v[180:183], v139 offset:18432
	ds_read_b128 v[184:187], v139 offset:19456
	ds_read_b128 v[188:191], v139 offset:20480
	ds_read_b128 v[192:195], v139 offset:21504
	ds_read_b128 v[196:199], v139 offset:22528
	ds_read_b128 v[200:203], v139 offset:23552
	global_load_lds_dwordx4 v[204:205], off
	s_add_i32 m0, s28, 0x2000
	s_add_u32 s28, s10, 0x80000
	v_lshl_add_u64 v[206:207], s[10:11], 0, v[130:131]
	s_addc_u32 s29, s11, 0
	s_add_i32 s27, s27, s14
	global_load_lds_dwordx4 v[206:207], off
	v_lshl_add_u64 v[208:209], s[28:29], 0, v[128:129]
	s_mov_b32 m0, s27
	v_lshl_add_u64 v[210:211], s[12:13], 0, v[130:131]
	global_load_lds_dwordx4 v[208:209], off
	v_lshl_add_u64 v[208:209], s[28:29], 0, v[130:131]
	s_add_i32 m0, s27, 0x2000
	s_nop 0
	global_load_lds_dwordx4 v[208:209], off
	v_lshl_add_u64 v[208:209], s[12:13], 0, v[128:129]
	s_mov_b32 m0, s15
	s_nop 0
	global_load_lds_dwordx4 v[208:209], off
	s_mov_b32 m0, s16
	s_nop 0
	global_load_lds_dwordx4 v[210:211], off
	s_waitcnt vmcnt(8)
	s_waitcnt lgkmcnt(0)
	s_barrier
; #define PG8_STAGE(bufoff, gbase, voff) do { _Pragma("unroll") for (int _i = 0; _i < 2; ++_i) \
;         __builtin_amdgcn_global_load_lds((const unsigned*)((const char*)(gbase) + (voff)[_i]), (PG8_LAS unsigned*)(lds + (bufoff) + ldsw + _i * 8192), 16, 0, 0); } while (0)
; #define PG8_LDA(dst, b, h) do { _Pragma("unroll") for (int m = 0; m < 4; ++m) _Pragma("unroll") for (int k = 0; k < 2; ++k) dst[m][k] = *(const PG8_LAS bf16x8*)(lds + PG8_SA(b, h) + aoff + m * 2048 + k * 1024); } while (0)
; #define PG8_LDB(dst, b, h) do { _Pragma("unroll") for (int n = 0; n < 2; ++n) _Pragma("unroll") for (int k = 0; k < 2; ++k) dst[n][k] = *(const PG8_LAS bf16x8*)(lds + PG8_SB(b, h) + boff + n * 2048 + k * 1024); } while (0)
; #define PG8_MMA(ai, bj, At, Bt) do { __builtin_amdgcn_s_setprio(1); _Pragma("unroll") for (int m = 0; m < 4; ++m) _Pragma("unroll") for (int n = 0; n < 2; ++n) _Pragma("unroll") for (int k = 0; k < 2; ++k) \
;         acc[ai][bj][m][n] = __builtin_amdgcn_mfma_f32_16x16x32_bf16(Bt[n][k], At[m][k], acc[ai][bj][m][n], 0, 0, 0); __builtin_amdgcn_s_setprio(0); } while (0)
; #define PG8_WAIT_V(n) asm volatile("s_waitcnt vmcnt(" #n ")" ::: "memory")
; #define PG8_WAIT_L(n) asm volatile("s_waitcnt lgkmcnt(" #n ")" ::: "memory")
; #define PG8_BAR __builtin_amdgcn_s_barrier()
; #define PG8_SCHED __builtin_amdgcn_sched_barrier(0)
; template <class Epi, class Sched, bool ALIGN_EPI = false, bool SP2 = false>
; __device__ __forceinline__ void gemm_phase(PG8_LAS unsigned char* lds, const Gemm g, const Sched& S, const Epi& E) {
;     ...
;             PG8_WAIT_V(8); PG8_WAIT_L(0); PG8_BAR; PG8_MMA(1, 0, At, B0); PG8_MMA(1, 1, At, B1); PG8_BAR; PG8_SCHED;
;             PG8_LDB(B0, 1, 0); PG8_LDB(B1, 1, 1); PG8_SCHED; PG8_LDA(At, 1, 0); PG8_STAGE(PG8_SA(0, 1), a2 + hstep, voffA);
;             PG8_WAIT_V(8); PG8_WAIT_L(0); PG8_BAR; PG8_MMA(0, 0, At, B0); PG8_MMA(0, 1, At, B1); PG8_BAR; PG8_SCHED;
	v_mfma_f32_16x16x32_bf16 v[60:63], v[140:143], v[172:175], v[60:63]
	v_mfma_f32_16x16x32_bf16 v[56:59], v[148:151], v[172:175], v[56:59]
	v_mfma_f32_16x16x32_bf16 v[52:55], v[140:143], v[180:183], v[52:55]
	v_mfma_f32_16x16x32_bf16 v[48:51], v[148:151], v[180:183], v[48:51]
	v_mfma_f32_16x16x32_bf16 v[36:39], v[140:143], v[188:191], v[36:39]
	v_mfma_f32_16x16x32_bf16 v[32:35], v[148:151], v[188:191], v[32:35]
	v_mfma_f32_16x16x32_bf16 v[20:23], v[140:143], v[196:199], v[20:23]
	v_mfma_f32_16x16x32_bf16 v[16:19], v[148:151], v[196:199], v[16:19]
	v_mfma_f32_16x16x32_bf16 v[60:63], v[144:147], v[176:179], v[60:63]
	v_mfma_f32_16x16x32_bf16 v[56:59], v[152:155], v[176:179], v[56:59]
	v_mfma_f32_16x16x32_bf16 v[52:55], v[144:147], v[184:187], v[52:55]
	v_mfma_f32_16x16x32_bf16 v[48:51], v[152:155], v[184:187], v[48:51]
	v_mfma_f32_16x16x32_bf16 v[36:39], v[144:147], v[192:195], v[36:39]
	v_mfma_f32_16x16x32_bf16 v[32:35], v[152:155], v[192:195], v[32:35]
	v_mfma_f32_16x16x32_bf16 v[20:23], v[144:147], v[200:203], v[20:23]
	v_mfma_f32_16x16x32_bf16 v[16:19], v[152:155], v[200:203], v[16:19]
	v_mfma_f32_16x16x32_bf16 v[44:47], v[156:159], v[172:175], v[44:47]
	v_mfma_f32_16x16x32_bf16 v[40:43], v[164:167], v[172:175], v[40:43]
	v_mfma_f32_16x16x32_bf16 v[28:31], v[156:159], v[180:183], v[28:31]
	v_mfma_f32_16x16x32_bf16 v[24:27], v[164:167], v[180:183], v[24:27]
	v_mfma_f32_16x16x32_bf16 v[12:15], v[156:159], v[188:191], v[12:15]
	v_mfma_f32_16x16x32_bf16 v[8:11], v[164:167], v[188:191], v[8:11]
	v_mfma_f32_16x16x32_bf16 v[4:7], v[156:159], v[196:199], v[4:7]
	v_mfma_f32_16x16x32_bf16 v[0:3], v[164:167], v[196:199], v[0:3]
	v_mfma_f32_16x16x32_bf16 v[44:47], v[160:163], v[176:179], v[44:47]
	v_mfma_f32_16x16x32_bf16 v[40:43], v[168:171], v[176:179], v[40:43]
	v_mfma_f32_16x16x32_bf16 v[28:31], v[160:163], v[184:187], v[28:31]
	v_mfma_f32_16x16x32_bf16 v[24:27], v[168:171], v[184:187], v[24:27]
	v_mfma_f32_16x16x32_bf16 v[12:15], v[160:163], v[192:195], v[12:15]
	v_mfma_f32_16x16x32_bf16 v[8:11], v[168:171], v[192:195], v[8:11]
	v_mfma_f32_16x16x32_bf16 v[4:7], v[160:163], v[200:203], v[4:7]
	v_mfma_f32_16x16x32_bf16 v[0:3], v[168:171], v[200:203], v[0:3]
	s_barrier
	s_add_i32 s27, 0, 0x18000
	s_add_i32 s28, 0, 0x1c000
	v_add_u32_e32 v152, s27, v138
	v_add_u32_e32 v168, s28, v138
	ds_read_b128 v[140:143], v152
	ds_read_b128 v[144:147], v152 offset:1024
	ds_read_b128 v[148:151], v152 offset:2048
	ds_read_b128 v[152:155], v152 offset:3072
	ds_read_b128 v[156:159], v168
	ds_read_b128 v[160:163], v168 offset:1024
	ds_read_b128 v[164:167], v168 offset:2048
	ds_read_b128 v[168:171], v168 offset:3072
	s_add_u32 s12, s12, 0x80000
	s_addc_u32 s13, s13, 0
	s_mov_b32 m0, s17
	v_lshl_add_u64 v[212:213], s[12:13], 0, v[128:129]
	ds_read_b128 v[172:175], v139 offset:32768
	ds_read_b128 v[176:179], v139 offset:33792
	ds_read_b128 v[180:183], v139 offset:34816
	ds_read_b128 v[184:187], v139 offset:35840
	ds_read_b128 v[188:191], v139 offset:36864
	ds_read_b128 v[192:195], v139 offset:37888
	ds_read_b128 v[196:199], v139 offset:38912
	ds_read_b128 v[200:203], v139 offset:39936
	global_load_lds_dwordx4 v[212:213], off
	v_lshl_add_u64 v[212:213], s[12:13], 0, v[130:131]
	s_mov_b32 m0, s18
	s_nop 0
	global_load_lds_dwordx4 v[212:213], off
	s_waitcnt vmcnt(8)
	s_waitcnt lgkmcnt(0)
	s_barrier
	v_mfma_f32_16x16x32_bf16 v[124:127], v[140:143], v[172:175], v[124:127]
	v_mfma_f32_16x16x32_bf16 v[120:123], v[148:151], v[172:175], v[120:123]
	v_mfma_f32_16x16x32_bf16 v[116:119], v[140:143], v[180:183], v[116:119]
	v_mfma_f32_16x16x32_bf16 v[112:115], v[148:151], v[180:183], v[112:115]
	v_mfma_f32_16x16x32_bf16 v[104:107], v[140:143], v[188:191], v[104:107]
	v_mfma_f32_16x16x32_bf16 v[96:99], v[148:151], v[188:191], v[96:99]
	v_mfma_f32_16x16x32_bf16 v[88:91], v[140:143], v[196:199], v[88:91]
	v_mfma_f32_16x16x32_bf16 v[80:83], v[148:151], v[196:199], v[80:83]
	v_mfma_f32_16x16x32_bf16 v[124:127], v[144:147], v[176:179], v[124:127]
	v_mfma_f32_16x16x32_bf16 v[120:123], v[152:155], v[176:179], v[120:123]
	v_mfma_f32_16x16x32_bf16 v[116:119], v[144:147], v[184:187], v[116:119]
	v_mfma_f32_16x16x32_bf16 v[112:115], v[152:155], v[184:187], v[112:115]
	v_mfma_f32_16x16x32_bf16 v[104:107], v[144:147], v[192:195], v[104:107]
	v_mfma_f32_16x16x32_bf16 v[96:99], v[152:155], v[192:195], v[96:99]
	v_mfma_f32_16x16x32_bf16 v[88:91], v[144:147], v[200:203], v[88:91]
	v_mfma_f32_16x16x32_bf16 v[80:83], v[152:155], v[200:203], v[80:83]
	v_mfma_f32_16x16x32_bf16 v[108:111], v[156:159], v[172:175], v[108:111]
	v_mfma_f32_16x16x32_bf16 v[100:103], v[164:167], v[172:175], v[100:103]
	v_mfma_f32_16x16x32_bf16 v[92:95], v[156:159], v[180:183], v[92:95]
	v_mfma_f32_16x16x32_bf16 v[84:87], v[164:167], v[180:183], v[84:87]
	v_mfma_f32_16x16x32_bf16 v[76:79], v[156:159], v[188:191], v[76:79]
	v_mfma_f32_16x16x32_bf16 v[72:75], v[164:167], v[188:191], v[72:75]
	v_mfma_f32_16x16x32_bf16 v[68:71], v[156:159], v[196:199], v[68:71]
	v_mfma_f32_16x16x32_bf16 v[64:67], v[164:167], v[196:199], v[64:67]
	v_mfma_f32_16x16x32_bf16 v[108:111], v[160:163], v[176:179], v[108:111]
	v_mfma_f32_16x16x32_bf16 v[100:103], v[168:171], v[176:179], v[100:103]
	v_mfma_f32_16x16x32_bf16 v[92:95], v[160:163], v[184:187], v[92:95]
	v_mfma_f32_16x16x32_bf16 v[84:87], v[168:171], v[184:187], v[84:87]
	v_mfma_f32_16x16x32_bf16 v[76:79], v[160:163], v[192:195], v[76:79]
	v_mfma_f32_16x16x32_bf16 v[72:75], v[168:171], v[192:195], v[72:75]
	v_mfma_f32_16x16x32_bf16 v[68:71], v[160:163], v[200:203], v[68:71]
	v_mfma_f32_16x16x32_bf16 v[64:67], v[168:171], v[200:203], v[64:67]
	s_barrier
; #define PG8_STAGE(bufoff, gbase, voff) do { _Pragma("unroll") for (int _i = 0; _i < 2; ++_i) \
;         __builtin_amdgcn_global_load_lds((const unsigned*)((const char*)(gbase) + (voff)[_i]), (PG8_LAS unsigned*)(lds + (bufoff) + ldsw + _i * 8192), 16, 0, 0); } while (0)
; #define PG8_LDA(dst, b, h) do { _Pragma("unroll") for (int m = 0; m < 4; ++m) _Pragma("unroll") for (int k = 0; k < 2; ++k) dst[m][k] = *(const PG8_LAS bf16x8*)(lds + PG8_SA(b, h) + aoff + m * 2048 + k * 1024); } while (0)
; #define PG8_MMA(ai, bj, At, Bt) do { __builtin_amdgcn_s_setprio(1); _Pragma("unroll") for (int m = 0; m < 4; ++m) _Pragma("unroll") for (int n = 0; n < 2; ++n) _Pragma("unroll") for (int k = 0; k < 2; ++k) \
;         acc[ai][bj][m][n] = __builtin_amdgcn_mfma_f32_16x16x32_bf16(Bt[n][k], At[m][k], acc[ai][bj][m][n], 0, 0, 0); __builtin_amdgcn_s_setprio(0); } while (0)
; #define PG8_WAIT_V(n) asm volatile("s_waitcnt vmcnt(" #n ")" ::: "memory")
; #define PG8_WAIT_L(n) asm volatile("s_waitcnt lgkmcnt(" #n ")" ::: "memory")
; #define PG8_BAR __builtin_amdgcn_s_barrier()
; #define PG8_SCHED __builtin_amdgcn_sched_barrier(0)
; template <class Epi, class Sched, bool ALIGN_EPI = false, bool SP2 = false>
; __device__ __forceinline__ void gemm_phase(PG8_LAS unsigned char* lds, const Gemm g, const Sched& S, const Epi& E) {
;     ...
;             PG8_LDA(At, 1, 1); PG8_STAGE(PG8_SB(1, 0), b3, voffB); PG8_STAGE(PG8_SB(1, 1), b3 + hstep, voffB); PG8_STAGE(PG8_SA(1, 0), a3, voffA);
;             PG8_WAIT_V(8); PG8_WAIT_L(0); PG8_BAR; PG8_MMA(1, 0, At, B0); PG8_MMA(1, 1, At, B1); PG8_BAR; PG8_SCHED;
;     ...
;         if constexpr (ALIGN_EPI) { if (wr == 0) PG8_BAR; }
	s_add_i32 s12, s27, s14
	v_lshl_add_u64 v[204:205], v[204:205], 0, s[76:77]
	s_mov_b32 m0, s12
	ds_read_b128 v[172:175], v139 offset:49152
	ds_read_b128 v[176:179], v139 offset:50176
	ds_read_b128 v[180:183], v139 offset:51200
	ds_read_b128 v[184:187], v139 offset:52224
	ds_read_b128 v[188:191], v139 offset:53248
	ds_read_b128 v[192:195], v139 offset:54272
	ds_read_b128 v[196:199], v139 offset:55296
	ds_read_b128 v[200:203], v139 offset:56320
	global_load_lds_dwordx4 v[204:205], off
	s_add_i32 m0, s12, 0x2000
	s_add_u32 s10, s10, 0x80080
	v_lshl_add_u64 v[204:205], v[206:207], 0, s[76:77]
	s_addc_u32 s11, s11, 0
	s_add_i32 s12, s28, s14
	global_load_lds_dwordx4 v[204:205], off
	v_lshl_add_u64 v[204:205], s[10:11], 0, v[128:129]
	s_mov_b32 m0, s12
	s_nop 0
	global_load_lds_dwordx4 v[204:205], off
	v_lshl_add_u64 v[204:205], s[10:11], 0, v[130:131]
	s_add_i32 m0, s12, 0x2000
	s_nop 0
	global_load_lds_dwordx4 v[204:205], off
	v_lshl_add_u64 v[204:205], v[208:209], 0, s[76:77]
	s_mov_b32 m0, s20
	s_nop 0
	global_load_lds_dwordx4 v[204:205], off
	v_lshl_add_u64 v[204:205], v[210:211], 0, s[76:77]
	s_mov_b32 m0, s21
	s_nop 0
	global_load_lds_dwordx4 v[204:205], off
	s_waitcnt vmcnt(8)
	s_waitcnt lgkmcnt(0)
	s_barrier
	v_mfma_f32_16x16x32_bf16 v[60:63], v[140:143], v[172:175], v[60:63]
	v_mfma_f32_16x16x32_bf16 v[56:59], v[148:151], v[172:175], v[56:59]
	v_mfma_f32_16x16x32_bf16 v[52:55], v[140:143], v[180:183], v[52:55]
	v_mfma_f32_16x16x32_bf16 v[48:51], v[148:151], v[180:183], v[48:51]
	v_mfma_f32_16x16x32_bf16 v[36:39], v[140:143], v[188:191], v[36:39]
	v_mfma_f32_16x16x32_bf16 v[32:35], v[148:151], v[188:191], v[32:35]
	v_mfma_f32_16x16x32_bf16 v[20:23], v[140:143], v[196:199], v[20:23]
	v_mfma_f32_16x16x32_bf16 v[16:19], v[148:151], v[196:199], v[16:19]
	v_mfma_f32_16x16x32_bf16 v[60:63], v[144:147], v[176:179], v[60:63]
	v_mfma_f32_16x16x32_bf16 v[56:59], v[152:155], v[176:179], v[56:59]
	v_mfma_f32_16x16x32_bf16 v[52:55], v[144:147], v[184:187], v[52:55]
	v_mfma_f32_16x16x32_bf16 v[48:51], v[152:155], v[184:187], v[48:51]
	v_mfma_f32_16x16x32_bf16 v[36:39], v[144:147], v[192:195], v[36:39]
	v_mfma_f32_16x16x32_bf16 v[32:35], v[152:155], v[192:195], v[32:35]
	v_mfma_f32_16x16x32_bf16 v[20:23], v[144:147], v[200:203], v[20:23]
	v_mfma_f32_16x16x32_bf16 v[16:19], v[152:155], v[200:203], v[16:19]
	v_mfma_f32_16x16x32_bf16 v[44:47], v[156:159], v[172:175], v[44:47]
	v_mfma_f32_16x16x32_bf16 v[40:43], v[164:167], v[172:175], v[40:43]
	v_mfma_f32_16x16x32_bf16 v[28:31], v[156:159], v[180:183], v[28:31]
	v_mfma_f32_16x16x32_bf16 v[24:27], v[164:167], v[180:183], v[24:27]
	v_mfma_f32_16x16x32_bf16 v[12:15], v[156:159], v[188:191], v[12:15]
	v_mfma_f32_16x16x32_bf16 v[8:11], v[164:167], v[188:191], v[8:11]
	v_mfma_f32_16x16x32_bf16 v[4:7], v[156:159], v[196:199], v[4:7]
	v_mfma_f32_16x16x32_bf16 v[0:3], v[164:167], v[196:199], v[0:3]
	v_mfma_f32_16x16x32_bf16 v[44:47], v[160:163], v[176:179], v[44:47]
	v_mfma_f32_16x16x32_bf16 v[40:43], v[168:171], v[176:179], v[40:43]
	v_mfma_f32_16x16x32_bf16 v[28:31], v[160:163], v[184:187], v[28:31]
	v_mfma_f32_16x16x32_bf16 v[24:27], v[168:171], v[184:187], v[24:27]
	v_mfma_f32_16x16x32_bf16 v[12:15], v[160:163], v[192:195], v[12:15]
	v_mfma_f32_16x16x32_bf16 v[8:11], v[168:171], v[192:195], v[8:11]
	v_mfma_f32_16x16x32_bf16 v[4:7], v[160:163], v[200:203], v[4:7]
	v_mfma_f32_16x16x32_bf16 v[0:3], v[168:171], v[200:203], v[0:3]
	s_barrier
	s_add_i32 s26, s26, 2
	s_add_u32 s8, s8, 0x100
	s_addc_u32 s9, s9, 0
	s_cmp_gt_u32 s26, 29
	s_cbranch_scc0 .LBB0_645
	s_cmpk_lt_u32 s1, 0x100
	s_cbranch_scc0 .LBB0_648
	s_barrier
